# V fragment tiles re-laid out [dt][s][lane] so each attn_run V fragment load is one contiguous 1 KB request per wave (producer relayout + 12 consumer sites + NSA LDS staging of VS/VW adapted)
# speedup vs baseline: 1.1678x; 1.0025x over previous
.LBB0_383:
	s_or_b64 exec, exec, s[0:1]
	s_waitcnt vmcnt(32)
	v_lshlrev_b32_e32 v44, 16, v44
	v_lshlrev_b32_e32 v28, 16, v28
	s_waitcnt vmcnt(30)
	v_lshlrev_b32_e32 v45, 16, v45
	v_or_b32_sdwa v21, v44, v21 dst_sel:DWORD dst_unused:UNUSED_PAD src0_sel:DWORD src1_sel:WORD_0
	v_lshlrev_b32_e32 v30, 16, v30
	v_or_b32_sdwa v22, v28, v22 dst_sel:DWORD dst_unused:UNUSED_PAD src0_sel:DWORD src1_sel:WORD_0
	v_or_b32_e32 v44, v63, v26
	v_mad_i32_i24 v28, v0, v27, v56
	s_movk_i32 s12, 0xe00
	v_or_b32_sdwa v24, v30, v24 dst_sel:DWORD dst_unused:UNUSED_PAD src0_sel:DWORD src1_sel:WORD_0
	v_lshlrev_b32_e32 v29, 16, v29
	v_mad_u64_u32 v[26:27], s[0:1], v28, s12, v[44:45]
	v_add_u32_e32 v30, v28, v0
	v_or_b32_sdwa v23, v29, v23 dst_sel:DWORD dst_unused:UNUSED_PAD src0_sel:DWORD src1_sel:WORD_0
	v_mad_u64_u32 v[28:29], s[0:1], v30, s12, v[44:45]
	v_mov_b32_e32 v27, v1
	v_lshlrev_b32_e32 v31, 16, v31
	v_lshl_add_u64 v[26:27], v[26:27], 1, s[66:67]
	v_mov_b32_e32 v29, v1
	v_or_b32_sdwa v25, v31, v25 dst_sel:DWORD dst_unused:UNUSED_PAD src0_sel:DWORD src1_sel:WORD_0
	global_load_ushort v31, v[26:27], off
	v_lshl_add_u64 v[26:27], v[28:29], 1, s[66:67]
	global_load_ushort v26, v[26:27], off
	v_lshlrev_b32_e32 v32, 16, v32
	v_add_u32_e32 v27, v30, v0
	v_or_b32_sdwa v18, v32, v18 dst_sel:DWORD dst_unused:UNUSED_PAD src0_sel:DWORD src1_sel:WORD_0
	v_mad_u64_u32 v[28:29], s[0:1], v27, s12, v[44:45]
	v_add_u32_e32 v32, v27, v0
	v_mov_b32_e32 v29, v1
	v_lshl_add_u64 v[28:29], v[28:29], 1, s[66:67]
	global_load_ushort v27, v[28:29], off
	v_lshlrev_b32_e32 v33, 16, v33
	v_or_b32_sdwa v19, v33, v19 dst_sel:DWORD dst_unused:UNUSED_PAD src0_sel:DWORD src1_sel:WORD_0
	v_lshlrev_b32_e32 v43, 16, v43
	v_or_b32_sdwa v20, v43, v20 dst_sel:DWORD dst_unused:UNUSED_PAD src0_sel:DWORD src1_sel:WORD_0
	v_or_b32_sdwa v14, v45, v14 dst_sel:DWORD dst_unused:UNUSED_PAD src0_sel:DWORD src1_sel:WORD_0
	s_waitcnt vmcnt(29)
	v_lshlrev_b32_e32 v47, 16, v47
	v_lshlrev_b32_e32 v46, 16, v46
	v_or_b32_sdwa v16, v47, v16 dst_sel:DWORD dst_unused:UNUSED_PAD src0_sel:DWORD src1_sel:WORD_0
	v_or_b32_sdwa v15, v46, v15 dst_sel:DWORD dst_unused:UNUSED_PAD src0_sel:DWORD src1_sel:WORD_0
	s_waitcnt vmcnt(3)
	v_lshlrev_b32_e32 v2, 16, v67
	v_lshlrev_b32_e32 v6, 16, v58
	v_or_b32_sdwa v5, v2, v66 dst_sel:DWORD dst_unused:UNUSED_PAD src0_sel:DWORD src1_sel:WORD_0
	v_lshlrev_b32_e32 v2, 16, v65
	v_or_b32_sdwa v9, v6, v9 dst_sel:DWORD dst_unused:UNUSED_PAD src0_sel:DWORD src1_sel:WORD_0
	v_lshlrev_b32_e32 v6, 16, v57
	v_or_b32_sdwa v4, v2, v64 dst_sel:DWORD dst_unused:UNUSED_PAD src0_sel:DWORD src1_sel:WORD_0
	v_lshlrev_b32_e32 v2, 16, v62
	v_or_b32_sdwa v8, v6, v8 dst_sel:DWORD dst_unused:UNUSED_PAD src0_sel:DWORD src1_sel:WORD_0
	v_lshlrev_b32_e32 v6, 16, v55
	v_lshlrev_b32_e32 v50, 16, v50
	v_lshlrev_b32_e32 v49, 16, v49
	v_lshlrev_b32_e32 v48, 16, v48
	v_or_b32_sdwa v3, v2, v61 dst_sel:DWORD dst_unused:UNUSED_PAD src0_sel:DWORD src1_sel:WORD_0
	v_lshlrev_b32_e32 v2, 16, v60
	v_or_b32_sdwa v7, v6, v7 dst_sel:DWORD dst_unused:UNUSED_PAD src0_sel:DWORD src1_sel:WORD_0
	v_lshlrev_b32_e32 v6, 16, v54
	v_lshlrev_b32_e32 v52, 16, v52
	v_lshlrev_b32_e32 v51, 16, v51
	v_or_b32_sdwa v11, v50, v11 dst_sel:DWORD dst_unused:UNUSED_PAD src0_sel:DWORD src1_sel:WORD_0
	v_or_b32_sdwa v10, v49, v10 dst_sel:DWORD dst_unused:UNUSED_PAD src0_sel:DWORD src1_sel:WORD_0
	v_or_b32_sdwa v17, v48, v17 dst_sel:DWORD dst_unused:UNUSED_PAD src0_sel:DWORD src1_sel:WORD_0
	v_or_b32_sdwa v2, v2, v59 dst_sel:DWORD dst_unused:UNUSED_PAD src0_sel:DWORD src1_sel:WORD_0
	v_or_b32_sdwa v6, v6, v53 dst_sel:DWORD dst_unused:UNUSED_PAD src0_sel:DWORD src1_sel:WORD_0
	v_or_b32_sdwa v13, v52, v13 dst_sel:DWORD dst_unused:UNUSED_PAD src0_sel:DWORD src1_sel:WORD_0
	v_or_b32_sdwa v12, v51, v12 dst_sel:DWORD dst_unused:UNUSED_PAD src0_sel:DWORD src1_sel:WORD_0
	s_waitcnt vmcnt(1)
	v_lshl_or_b32 v26, v26, 16, v31
	v_mad_u64_u32 v[30:31], s[0:1], v32, s12, v[44:45]
	v_mov_b32_e32 v31, v1
	v_lshl_add_u64 v[28:29], v[30:31], 1, s[66:67]
	global_load_ushort v28, v[28:29], off
	v_mad_i32_i24 v30, v0, 5, v32
	v_add_u32_e32 v32, v30, v0
	s_waitcnt vmcnt(0)
	v_lshl_or_b32 v27, v28, 16, v27
	v_mad_u64_u32 v[28:29], s[0:1], v30, s12, v[44:45]
	v_mad_u64_u32 v[30:31], s[0:1], v32, s12, v[44:45]
	v_mov_b32_e32 v29, v1
	v_lshl_add_u64 v[28:29], v[28:29], 1, s[66:67]
	v_mov_b32_e32 v31, v1
	global_load_ushort v33, v[28:29], off
	v_lshl_add_u64 v[28:29], v[30:31], 1, s[66:67]
	global_load_ushort v28, v[28:29], off
	v_add_u32_e32 v29, v32, v0
	v_mad_u64_u32 v[30:31], s[0:1], v29, s12, v[44:45]
	v_add_u32_e32 v43, v29, v0
	v_mov_b32_e32 v31, v1
	v_lshl_add_u64 v[30:31], v[30:31], 1, s[66:67]
	global_load_ushort v29, v[30:31], off
	s_waitcnt vmcnt(1)
	v_lshl_or_b32 v28, v28, 16, v33
	v_mad_u64_u32 v[32:33], s[0:1], v43, s12, v[44:45]
	v_mov_b32_e32 v33, v1
	v_lshl_add_u64 v[30:31], v[32:33], 1, s[66:67]
	global_load_ushort v30, v[30:31], off
	v_mad_i32_i24 v32, v0, 5, v43
	v_add_u32_e32 v43, v32, v0
	s_waitcnt vmcnt(0)
	v_lshl_or_b32 v29, v30, 16, v29
	v_mad_u64_u32 v[30:31], s[0:1], v32, s12, v[44:45]
	v_mov_b32_e32 v31, v1
	v_lshl_add_u64 v[30:31], v[30:31], 1, s[66:67]
	v_mad_u64_u32 v[32:33], s[0:1], v43, s12, v[44:45]
	global_load_ushort v45, v[30:31], off
	v_mov_b32_e32 v33, v1
	v_lshl_add_u64 v[30:31], v[32:33], 1, s[66:67]
	global_load_ushort v30, v[30:31], off
	v_add_u32_e32 v31, v43, v0
	v_add_u32_e32 v43, v31, v0
	s_waitcnt vmcnt(1)
	v_mad_u64_u32 v[32:33], s[0:1], v31, s12, v[44:45]
	v_mad_u64_u32 v[46:47], s[0:1], v43, s12, v[44:45]
	v_mov_b32_e32 v33, v1
	v_lshl_add_u64 v[32:33], v[32:33], 1, s[66:67]
	v_mov_b32_e32 v47, v1
	global_load_ushort v31, v[32:33], off
	v_lshl_add_u64 v[32:33], v[46:47], 1, s[66:67]
	global_load_ushort v32, v[32:33], off
	v_mad_i32_i24 v43, v0, 5, v43
	s_waitcnt vmcnt(2)
	v_lshl_or_b32 v30, v30, 16, v45
	s_waitcnt vmcnt(0)
	v_lshl_or_b32 v31, v32, 16, v31
	v_mad_u64_u32 v[32:33], s[0:1], v43, s12, v[44:45]
	v_add_u32_e32 v43, v43, v0
	v_mad_u64_u32 v[46:47], s[0:1], v43, s12, v[44:45]
	v_mov_b32_e32 v33, v1
	v_lshl_add_u64 v[32:33], v[32:33], 1, s[66:67]
	v_mov_b32_e32 v47, v1
	global_load_ushort v45, v[32:33], off
	v_lshl_add_u64 v[32:33], v[46:47], 1, s[66:67]
	global_load_ushort v32, v[32:33], off
	v_add_u32_e32 v33, v43, v0
	v_add_u32_e32 v0, v33, v0
	s_waitcnt vmcnt(1)
	v_mad_u64_u32 v[46:47], s[0:1], v33, s12, v[44:45]
	s_waitcnt vmcnt(0)
	v_lshl_or_b32 v32, v32, 16, v45
	v_mad_u64_u32 v[44:45], s[0:1], v0, s12, v[44:45]
	v_mov_b32_e32 v47, v1
	v_mov_b32_e32 v45, v1
	v_lshl_add_u64 v[46:47], v[46:47], 1, s[66:67]
	v_lshl_add_u64 v[44:45], v[44:45], 1, s[66:67]
	global_load_ushort v0, v[46:47], off
	global_load_ushort v33, v[44:45], off
	s_mov_b64 s[0:1], 0
	s_waitcnt vmcnt(0)
	v_lshl_or_b32 v33, v33, 16, v0
	v_lshlrev_b32_e32 v0, 4, v42
	v_and_b32_e32 v0, 0x3f0, v0
	v_lshl_add_u64 v[34:35], v[34:35], 0, v[0:1]
	global_store_dwordx4 v[34:35], v[22:25], off
	global_store_dwordx4 v[34:35], v[18:21], off offset:1024
	s_nop 1
	v_lshl_add_u64 v[18:19], v[36:37], 0, v[0:1]
	global_store_dwordx4 v[18:19], v[14:17], off
	global_store_dwordx4 v[18:19], v[10:13], off offset:1024
	s_nop 1
	v_lshl_add_u64 v[10:11], v[38:39], 0, v[0:1]
	global_store_dwordx4 v[10:11], v[6:9], off
	global_store_dwordx4 v[10:11], v[2:5], off offset:1024
	s_nop 1
	v_lshl_add_u64 v[2:3], v[40:41], 0, v[0:1]
	global_store_dwordx4 v[2:3], v[26:29], off
	global_store_dwordx4 v[2:3], v[30:33], off offset:1024

.LBB0_490:
	s_ashr_i32 s0, s42, 2
	s_and_b32 s0, s0, -8
	v_readlane_b32 s12, v254, 38
	s_add_i32 s38, s0, s12
	s_mul_hi_i32 s0, s38, 0x2aaaaaab
	s_lshr_b32 s1, s0, 31
	s_add_i32 s0, s0, s1
	s_mul_i32 s1, s0, 6
	s_sub_i32 s43, s38, s1
	s_lshl_b32 s1, s42, 7
	s_and_b32 s40, s1, 0xe00
	s_lshl_b32 s1, s42, 2
	v_mov_b32_e32 v0, v199
	s_and_b32 s1, s1, 12
	v_add_u32_e32 v162, s1, v161
	v_and_b32_e32 v175, 31, v0
	v_and_b32_e32 v174, 63, v0
	v_bfe_u32 v10, v0, 5, 1
	v_lshl_or_b32 v0, v175, 4, s40
	v_add_u32_e32 v2, v0, v162
	s_ashr_i32 s1, s0, 31
	s_lshl_b64 s[36:37], s[0:1], 12
	v_ashrrev_i32_e32 v3, 31, v2
	v_lshl_add_u64 v[158:159], s[36:37], 0, v[2:3]
	v_mov_b64_e32 v[2:3], s[66:67]
	v_mad_u64_u32 v[2:3], s[0:1], v158, s80, v[2:3]
	s_lshl_b32 s0, s43, 6
	v_mad_i32_i24 v3, v159, s80, v3
	s_ashr_i32 s1, s0, 31
	v_lshl_add_u64 v[4:5], s[0:1], 1, v[2:3]
	v_lshlrev_b32_e32 v0, 4, v10
	v_lshlrev_b32_e32 v160, 3, v10
	v_lshl_add_u64 v[4:5], v[4:5], 0, v[0:1]
	s_add_i32 s30, s0, 0x180
	s_ashr_i32 s39, s38, 31
	v_readlane_b32 s44, v253, 2
	global_load_dwordx4 v[82:85], v[4:5], off
	global_load_dwordx4 v[86:89], v[4:5], off offset:32
	global_load_dwordx4 v[90:93], v[4:5], off offset:64
	global_load_dwordx4 v[94:97], v[4:5], off offset:96
	v_or_b32_e32 v4, s30, v160
	s_lshl_b64 s[38:39], s[38:39], 19
	s_lshl_b32 s30, s40, 3
	v_readlane_b32 s48, v253, 6
	v_ashrrev_i32_e32 v163, 31, v162
	v_readlane_b32 s49, v253, 7
	s_add_u32 s38, s48, s38
	v_lshlrev_b64 v[6:7], 15, v[162:163]
	s_addc_u32 s39, s49, s39
	v_mov_b32_e32 v5, v1
	v_lshl_add_u64 v[6:7], s[38:39], 0, v[6:7]
	v_lshlrev_b64 v[4:5], 1, v[4:5]
	v_lshl_add_u64 v[8:9], v[6:7], 0, s[30:31]
	v_lshlrev_b32_e32 v0, 5, v174
	v_lshl_add_u64 v[2:3], v[2:3], 0, v[4:5]
	v_lshl_add_u64 v[8:9], v[8:9], 0, v[0:1]
	v_and_b32_e32 v238, 63, v199
	v_lshrrev_b32_e32 v239, 3, v238
	v_and_b32_e32 v240, 31, v238
	v_sub_u32_e32 v224, v239, v240
	v_add_u32_e32 v225, 8, v224
	v_add_u32_e32 v226, 16, v224
	v_add_u32_e32 v227, 24, v224
	v_lshrrev_b32_e32 v241, 5, v238
	v_and_b32_e32 v242, 7, v238
	v_lshrrev_b32_e32 v243, 4, v238
	v_xor_b32_e32 v228, v242, v243
	v_xor_b32_e32 v229, 4, v228
	v_sub_u32_e32 v228, v228, v241
	v_sub_u32_e32 v229, v229, v241
	v_lshlrev_b32_e32 v228, 4, v228
	v_lshlrev_b32_e32 v229, 4, v229
	v_lshrrev_b32_e32 v250, 6, v199
	v_lshlrev_b32_e32 v250, 13, v250
	v_bfe_u32 v251, v238, 1, 3
	v_xor_b32_e32 v251, v251, v241
	v_lshlrev_b32_e32 v251, 4, v251
	v_lshl_add_u32 v251, v240, 7, v251
	v_add_u32_e32 v234, v250, v251
	v_xor_b32_e32 v235, 0x20, v234
	v_xor_b32_e32 v236, 0x40, v234
	v_xor_b32_e32 v237, 0x60, v234
	v_readfirstlane_b32 s98, v250
	s_mov_b32 s99, 0x1c000
	s_add_u32 m0, s98, 0x0
	v_mad_i64_i32 v[232:233], s[100:101], v224, s99, v[2:3]
	v_add_u32_e32 v232, v228, v232
	global_load_lds_dwordx4 v[232:233], off
	s_add_u32 m0, s98, 0x400
	v_mad_i64_i32 v[232:233], s[100:101], v225, s99, v[2:3]
	v_add_u32_e32 v232, v229, v232
	global_load_lds_dwordx4 v[232:233], off
	s_add_u32 m0, s98, 0x800
	v_mad_i64_i32 v[232:233], s[100:101], v226, s99, v[2:3]
	v_add_u32_e32 v232, v228, v232
	global_load_lds_dwordx4 v[232:233], off
	s_add_u32 m0, s98, 0xc00
	v_mad_i64_i32 v[232:233], s[100:101], v227, s99, v[2:3]
	v_add_u32_e32 v232, v229, v232
	global_load_lds_dwordx4 v[232:233], off
	v_and_b32_e32 v230, 63, v199
	v_lshlrev_b32_e32 v230, 4, v230
	v_sub_u32_e32 v230, 0, v230
	v_ashrrev_i32_e32 v231, 31, v230
	v_lshl_add_u64 v[230:231], v[8:9], 0, v[230:231]
	global_load_dwordx4 v[110:113], v[230:231], off
	global_load_dwordx4 v[106:109], v[230:231], off offset:1024
	global_load_dwordx4 v[102:105], v[230:231], off offset:2048
	global_load_dwordx4 v[98:101], v[230:231], off offset:3072
	v_lshl_or_b32 v163, v10, 2, v213
	v_lshl_add_u64 v[164:165], v[6:7], 0, v[0:1]
	v_lshl_add_u64 v[166:167], s[66:67], 0, v[4:5]
	v_mov_b32_e32 v2, v1
	v_mov_b32_e32 v3, v1
	v_mov_b32_e32 v4, v1
	v_mov_b32_e32 v5, v1
	v_mov_b32_e32 v6, v1
	v_mov_b32_e32 v7, v1
	v_mov_b32_e32 v8, v1
	v_mov_b32_e32 v9, v1
	v_mov_b32_e32 v10, v1
	v_mov_b32_e32 v11, v1
	v_mov_b32_e32 v12, v1
	v_mov_b32_e32 v13, v1
	v_mov_b32_e32 v14, v1
	v_mov_b32_e32 v15, v1
	v_mov_b32_e32 v16, v1
	v_mov_b32_e32 v17, v1
	v_mov_b32_e32 v18, v1
	v_mov_b32_e32 v19, v1
	v_mov_b32_e32 v20, v1
	v_mov_b32_e32 v21, v1
	v_mov_b32_e32 v22, v1
	v_mov_b32_e32 v23, v1
	v_mov_b32_e32 v24, v1
	v_mov_b32_e32 v25, v1
	v_mov_b32_e32 v26, v1
	v_mov_b32_e32 v27, v1
	v_mov_b32_e32 v28, v1
	v_mov_b32_e32 v29, v1
	v_mov_b32_e32 v30, v1
	v_mov_b32_e32 v31, v1
	v_mov_b32_e32 v0, v1
	v_mov_b64_e32 v[32:33], v[30:31]
	s_lshr_b32 s30, s40, 4
	s_mov_b32 s44, 0
	v_mov_b32_e32 v173, 0xc61c4000
	v_mov_b32_e32 v171, 0
	v_mov_b64_e32 v[30:31], v[28:29]
	v_mov_b64_e32 v[28:29], v[26:27]
	v_mov_b64_e32 v[26:27], v[24:25]
	v_mov_b64_e32 v[24:25], v[22:23]
	v_mov_b64_e32 v[22:23], v[20:21]
	v_mov_b64_e32 v[20:21], v[18:19]
	v_mov_b64_e32 v[18:19], v[16:17]
	v_mov_b64_e32 v[16:17], v[14:15]
	v_mov_b64_e32 v[14:15], v[12:13]
	v_mov_b64_e32 v[12:13], v[10:11]
	v_mov_b64_e32 v[10:11], v[8:9]
	v_mov_b64_e32 v[8:9], v[6:7]
	v_mov_b64_e32 v[6:7], v[4:5]
	v_mov_b64_e32 v[4:5], v[2:3]
	v_mov_b64_e32 v[2:3], v[0:1]
	v_readlane_b32 s13, v254, 39
	v_readlane_b32 s45, v253, 3
	v_readlane_b32 s46, v253, 4
	v_readlane_b32 s47, v253, 5
	v_readlane_b32 s50, v253, 8
	v_readlane_b32 s51, v253, 9
	v_readlane_b32 s52, v253, 10
	v_readlane_b32 s53, v253, 11
	v_readlane_b32 s54, v253, 12
	v_readlane_b32 s55, v253, 13
	v_readlane_b32 s56, v253, 14
	v_readlane_b32 s57, v253, 15
	v_readlane_b32 s58, v253, 16
	v_readlane_b32 s59, v253, 17
	s_branch .LBB0_494

.LBB0_498:
	s_cmp_gt_i32 s45, -1
	s_cselect_b64 s[38:39], -1, 0
	s_cmp_lt_i32 s45, 0
	s_cselect_b32 s41, s44, s45
	s_lshl_b32 s41, s41, 5
	s_sub_i32 s41, s30, s41
	v_or_b32_e32 v0, s41, v175
	v_lshl_add_u32 v50, v0, 4, v162
	s_ashr_i32 s46, s41, 5
	s_ashr_i32 s47, s46, 31
	v_ashrrev_i32_e32 v51, 31, v50
	s_lshl_b64 s[46:47], s[46:47], 12
	v_lshl_add_u64 v[50:51], s[36:37], 0, v[50:51]
	v_lshl_add_u64 v[52:53], v[164:165], 0, s[46:47]
	v_mad_u64_u32 v[54:55], s[46:47], v50, s80, v[166:167]
	v_mad_i32_i24 v55, v51, s80, v55
	s_add_u32 m0, s98, 0x1000
	v_mad_i64_i32 v[232:233], s[100:101], v224, s99, v[54:55]
	v_add_u32_e32 v232, v228, v232
	global_load_lds_dwordx4 v[232:233], off
	s_add_u32 m0, s98, 0x1400
	v_mad_i64_i32 v[232:233], s[100:101], v225, s99, v[54:55]
	v_add_u32_e32 v232, v229, v232
	global_load_lds_dwordx4 v[232:233], off
	s_add_u32 m0, s98, 0x1800
	v_mad_i64_i32 v[232:233], s[100:101], v226, s99, v[54:55]
	v_add_u32_e32 v232, v228, v232
	global_load_lds_dwordx4 v[232:233], off
	s_add_u32 m0, s98, 0x1c00
	v_mad_i64_i32 v[232:233], s[100:101], v227, s99, v[54:55]
	v_add_u32_e32 v232, v229, v232
	global_load_lds_dwordx4 v[232:233], off
	v_and_b32_e32 v230, 63, v199
	v_lshlrev_b32_e32 v230, 4, v230
	v_sub_u32_e32 v230, 0, v230
	v_ashrrev_i32_e32 v231, 31, v230
	v_lshl_add_u64 v[230:231], v[52:53], 0, v[230:231]
	global_load_dwordx4 v[126:129], v[230:231], off
	global_load_dwordx4 v[122:125], v[230:231], off offset:1024
	global_load_dwordx4 v[118:121], v[230:231], off offset:2048
	global_load_dwordx4 v[114:117], v[230:231], off offset:3072
	s_waitcnt vmcnt(12)
	ds_read_b128 v[142:145], v234
	ds_read_b128 v[134:137], v235
	ds_read_b128 v[130:133], v236
	ds_read_b128 v[138:141], v237
	s_waitcnt lgkmcnt(3)
	v_mfma_f32_32x32x16_bf16 v[34:49], v[142:145], v[82:85], 0
	v_or_b32_e32 v0, s40, v175
	v_add_u32_e32 v50, 0xffffff7f, v0
	v_cmp_gt_u32_e32 vcc, s2, v50
	s_waitcnt lgkmcnt(2)
	v_mfma_f32_32x32x16_bf16 v[34:49], v[134:137], v[86:89], v[34:49]
	s_waitcnt lgkmcnt(1)
	v_mfma_f32_32x32x16_bf16 v[34:49], v[130:133], v[90:93], v[34:49]
	s_waitcnt lgkmcnt(0)
	v_mfma_f32_32x32x16_bf16 v[34:49], v[138:141], v[94:97], v[34:49]
	s_cbranch_vccz .LBB0_500
	v_sub_u32_e32 v0, v163, v0
	v_cmp_gt_u32_e32 vcc, s3, v0
	v_add_u32_e32 v50, 0xffffff80, v0
	s_nop 7
	v_cndmask_b32_e32 v34, v212, v34, vcc
	v_cmp_lt_u32_e32 vcc, s8, v50
	v_add_u32_e32 v50, 0xffffff81, v0
	s_nop 0
	v_cndmask_b32_e32 v35, v212, v35, vcc
	v_cmp_lt_u32_e32 vcc, s8, v50
	v_add_u32_e32 v50, 0xffffff82, v0
	s_nop 0
	v_cndmask_b32_e32 v36, v212, v36, vcc
	v_cmp_lt_u32_e32 vcc, s8, v50
	v_add_u32_e32 v50, 0xffffff87, v0
	s_nop 0
	v_cndmask_b32_e32 v37, v212, v37, vcc
	v_cmp_lt_u32_e32 vcc, s8, v50
	v_add_u32_e32 v50, 0xffffff88, v0
	s_nop 0
	v_cndmask_b32_e32 v38, v212, v38, vcc
	v_cmp_lt_u32_e32 vcc, s8, v50
	v_add_u32_e32 v50, 0xffffff89, v0
	s_nop 0
	v_cndmask_b32_e32 v39, v212, v39, vcc
	v_cmp_lt_u32_e32 vcc, s8, v50
	v_add_u32_e32 v50, 0xffffff8a, v0
	s_nop 0
	v_cndmask_b32_e32 v40, v212, v40, vcc
	v_cmp_lt_u32_e32 vcc, s8, v50
	v_add_u32_e32 v50, 0xffffff8f, v0
	s_nop 0
	v_cndmask_b32_e32 v41, v212, v41, vcc
	v_cmp_lt_u32_e32 vcc, s8, v50
	v_add_u32_e32 v50, 0xffffff90, v0
	s_nop 0
	v_cndmask_b32_e32 v42, v212, v42, vcc
	v_cmp_lt_u32_e32 vcc, s8, v50
	v_add_u32_e32 v50, 0xffffff91, v0
	s_nop 0
	v_cndmask_b32_e32 v43, v212, v43, vcc
	v_cmp_lt_u32_e32 vcc, s8, v50
	v_add_u32_e32 v50, 0xffffff92, v0
	s_nop 0
	v_cndmask_b32_e32 v44, v212, v44, vcc
	v_cmp_lt_u32_e32 vcc, s8, v50
	v_add_u32_e32 v50, 0xffffff97, v0
	s_nop 0
	v_cndmask_b32_e32 v45, v212, v45, vcc
	v_cmp_lt_u32_e32 vcc, s8, v50
	v_add_u32_e32 v50, 0xffffff98, v0
	s_nop 0
	v_cndmask_b32_e32 v46, v212, v46, vcc
	v_cmp_lt_u32_e32 vcc, s8, v50
	v_add_u32_e32 v50, 0xffffff99, v0
	v_add_u32_e32 v0, 0xffffff9a, v0
	v_cndmask_b32_e32 v47, v212, v47, vcc
	v_cmp_lt_u32_e32 vcc, s8, v50
	s_nop 1
	v_cndmask_b32_e32 v48, v212, v48, vcc
	v_cmp_lt_u32_e32 vcc, s8, v0
	s_nop 1
	v_cndmask_b32_e32 v49, v212, v49, vcc

.LBB0_508:
	s_cmp_lt_i32 s44, 0
	s_cselect_b64 s[38:39], -1, 0
	s_cmp_gt_i32 s44, -1
	s_cselect_b32 s41, s44, s45
	s_lshl_b32 s41, s41, 5
	s_sub_i32 s41, s30, s41
	v_or_b32_e32 v0, s41, v175
	v_lshl_add_u32 v2, v0, 4, v162
	s_ashr_i32 s46, s41, 5
	s_ashr_i32 s47, s46, 31
	v_ashrrev_i32_e32 v3, 31, v2
	s_lshl_b64 s[46:47], s[46:47], 12
	v_lshl_add_u64 v[2:3], s[36:37], 0, v[2:3]
	v_lshl_add_u64 v[4:5], v[164:165], 0, s[46:47]
	v_mad_u64_u32 v[6:7], s[46:47], v2, s80, v[166:167]
	v_mad_i32_i24 v7, v3, s80, v7
	s_add_u32 m0, s98, 0x0
	v_mad_i64_i32 v[232:233], s[100:101], v224, s99, v[6:7]
	v_add_u32_e32 v232, v228, v232
	global_load_lds_dwordx4 v[232:233], off
	s_add_u32 m0, s98, 0x400
	v_mad_i64_i32 v[232:233], s[100:101], v225, s99, v[6:7]
	v_add_u32_e32 v232, v229, v232
	global_load_lds_dwordx4 v[232:233], off
	s_add_u32 m0, s98, 0x800
	v_mad_i64_i32 v[232:233], s[100:101], v226, s99, v[6:7]
	v_add_u32_e32 v232, v228, v232
	global_load_lds_dwordx4 v[232:233], off
	s_add_u32 m0, s98, 0xc00
	v_mad_i64_i32 v[232:233], s[100:101], v227, s99, v[6:7]
	v_add_u32_e32 v232, v229, v232
	global_load_lds_dwordx4 v[232:233], off
	v_and_b32_e32 v230, 63, v199
	v_lshlrev_b32_e32 v230, 4, v230
	v_sub_u32_e32 v230, 0, v230
	v_ashrrev_i32_e32 v231, 31, v230
	v_lshl_add_u64 v[230:231], v[4:5], 0, v[230:231]
	global_load_dwordx4 v[110:113], v[230:231], off
	global_load_dwordx4 v[106:109], v[230:231], off offset:1024
	global_load_dwordx4 v[102:105], v[230:231], off offset:2048
	global_load_dwordx4 v[98:101], v[230:231], off offset:3072
	s_waitcnt vmcnt(12)
	ds_read_b128 v[66:69], v234 offset:4096
	ds_read_b128 v[154:157], v235 offset:4096
	ds_read_b128 v[150:153], v236 offset:4096
	ds_read_b128 v[146:149], v237 offset:4096
	s_waitcnt lgkmcnt(3)
	v_mfma_f32_32x32x16_bf16 v[66:81], v[66:69], v[82:85], 0
	v_or_b32_e32 v0, s40, v175
	v_add_u32_e32 v2, 0xffffff7f, v0
	v_cmp_gt_u32_e32 vcc, s2, v2
	s_waitcnt lgkmcnt(2)
	v_mfma_f32_32x32x16_bf16 v[66:81], v[154:157], v[86:89], v[66:81]
	s_waitcnt lgkmcnt(1)
	v_mfma_f32_32x32x16_bf16 v[66:81], v[150:153], v[90:93], v[66:81]
	s_waitcnt lgkmcnt(0)
	v_mfma_f32_32x32x16_bf16 v[66:81], v[146:149], v[94:97], v[66:81]
	s_cbranch_vccz .LBB0_510
	v_sub_u32_e32 v0, v163, v0
	v_cmp_gt_u32_e32 vcc, s3, v0
	v_add_u32_e32 v2, 0xffffff80, v0
	s_nop 7
	v_cndmask_b32_e32 v66, v212, v66, vcc
	v_cmp_lt_u32_e32 vcc, s8, v2
	v_add_u32_e32 v2, 0xffffff81, v0
	s_nop 0
	v_cndmask_b32_e32 v67, v212, v67, vcc
	v_cmp_lt_u32_e32 vcc, s8, v2
	v_add_u32_e32 v2, 0xffffff82, v0
	s_nop 0
	v_cndmask_b32_e32 v68, v212, v68, vcc
	v_cmp_lt_u32_e32 vcc, s8, v2
	v_add_u32_e32 v2, 0xffffff87, v0
	s_nop 0
	v_cndmask_b32_e32 v69, v212, v69, vcc
	v_cmp_lt_u32_e32 vcc, s8, v2
	v_add_u32_e32 v2, 0xffffff88, v0
	s_nop 0
	v_cndmask_b32_e32 v70, v212, v70, vcc
	v_cmp_lt_u32_e32 vcc, s8, v2
	v_add_u32_e32 v2, 0xffffff89, v0
	s_nop 0
	v_cndmask_b32_e32 v71, v212, v71, vcc
	v_cmp_lt_u32_e32 vcc, s8, v2
	v_add_u32_e32 v2, 0xffffff8a, v0
	s_nop 0
	v_cndmask_b32_e32 v72, v212, v72, vcc
	v_cmp_lt_u32_e32 vcc, s8, v2
	v_add_u32_e32 v2, 0xffffff8f, v0
	s_nop 0
	v_cndmask_b32_e32 v73, v212, v73, vcc
	v_cmp_lt_u32_e32 vcc, s8, v2
	v_add_u32_e32 v2, 0xffffff90, v0
	s_nop 0
	v_cndmask_b32_e32 v74, v212, v74, vcc
	v_cmp_lt_u32_e32 vcc, s8, v2
	v_add_u32_e32 v2, 0xffffff91, v0
	s_nop 0
	v_cndmask_b32_e32 v75, v212, v75, vcc
	v_cmp_lt_u32_e32 vcc, s8, v2
	v_add_u32_e32 v2, 0xffffff92, v0
	s_nop 0
	v_cndmask_b32_e32 v76, v212, v76, vcc
	v_cmp_lt_u32_e32 vcc, s8, v2
	v_add_u32_e32 v2, 0xffffff97, v0
	s_nop 0
	v_cndmask_b32_e32 v77, v212, v77, vcc
	v_cmp_lt_u32_e32 vcc, s8, v2
	v_add_u32_e32 v2, 0xffffff98, v0
	s_nop 0
	v_cndmask_b32_e32 v78, v212, v78, vcc
	v_cmp_lt_u32_e32 vcc, s8, v2
	v_add_u32_e32 v2, 0xffffff99, v0
	v_add_u32_e32 v0, 0xffffff9a, v0
	v_cndmask_b32_e32 v79, v212, v79, vcc
	v_cmp_lt_u32_e32 vcc, s8, v2
	s_nop 1
	v_cndmask_b32_e32 v80, v212, v80, vcc
	v_cmp_lt_u32_e32 vcc, s8, v0
	s_nop 1
	v_cndmask_b32_e32 v81, v212, v81, vcc

.LBB0_679:
	v_lshl_add_u32 v0, v138, 3, 0
	s_waitcnt lgkmcnt(0)
	s_barrier
	ds_read_b64 v[132:133], v0 offset:33280
	v_and_b32_e32 v0, 64, v216
	v_add_u32_e32 v0, 64, v0
	v_xor_b32_e32 v34, 1, v216
	v_cmp_lt_i32_e32 vcc, v34, v0
	v_xor_b32_e32 v36, 2, v216
	s_ashr_i32 s51, s44, 1
	v_cndmask_b32_e32 v34, v216, v34, vcc
	v_lshlrev_b32_e32 v34, 2, v34
	s_waitcnt lgkmcnt(0)
	ds_bpermute_b32 v35, v34, v132
	ds_bpermute_b32 v34, v34, v133
	v_cmp_lt_i32_e32 vcc, v36, v0
	s_cmp_lt_i32 s51, 0
	s_cselect_b64 s[38:39], -1, 0
	v_cndmask_b32_e32 v36, v216, v36, vcc
	s_waitcnt lgkmcnt(1)
	v_or_b32_e32 v35, v35, v132
	s_waitcnt lgkmcnt(0)
	v_or_b32_e32 v34, v34, v133
	v_lshlrev_b32_e32 v36, 2, v36
	ds_bpermute_b32 v37, v36, v35
	ds_bpermute_b32 v36, v36, v34
	v_mov_b32_e32 v65, 0
	v_mov_b32_e32 v66, v199
	v_mov_b32_e32 v64, v65
	s_waitcnt lgkmcnt(1)
	v_or_b32_e32 v35, v37, v35
	s_waitcnt lgkmcnt(0)
	v_or_b32_e32 v34, v36, v34
	v_xor_b32_e32 v36, 4, v216
	v_cmp_lt_i32_e32 vcc, v36, v0
	v_mov_b32_e32 v63, v65
	v_mov_b32_e32 v62, v65
	v_cndmask_b32_e32 v36, v216, v36, vcc
	v_lshlrev_b32_e32 v36, 2, v36
	ds_bpermute_b32 v37, v36, v35
	ds_bpermute_b32 v36, v36, v34
	v_mov_b32_e32 v61, v65
	v_mov_b32_e32 v60, v65
	v_mov_b32_e32 v59, v65
	s_waitcnt lgkmcnt(1)
	v_or_b32_e32 v35, v37, v35
	s_waitcnt lgkmcnt(0)
	v_or_b32_e32 v34, v36, v34
	v_xor_b32_e32 v36, 8, v216
	v_cmp_lt_i32_e32 vcc, v36, v0
	v_mov_b32_e32 v58, v65
	v_mov_b32_e32 v57, v65
	v_cndmask_b32_e32 v36, v216, v36, vcc
	v_lshlrev_b32_e32 v36, 2, v36
	ds_bpermute_b32 v37, v36, v35
	ds_bpermute_b32 v36, v36, v34
	v_mov_b32_e32 v56, v65
	v_mov_b32_e32 v55, v65
	v_mov_b32_e32 v54, v65
	s_waitcnt lgkmcnt(1)
	v_or_b32_e32 v35, v37, v35
	s_waitcnt lgkmcnt(0)
	v_or_b32_e32 v34, v36, v34
	v_xor_b32_e32 v36, 16, v216
	v_cmp_lt_i32_e32 vcc, v36, v0
	s_waitcnt vmcnt(0)
	v_mov_b32_e32 v53, v65
	v_mov_b32_e32 v52, v65
	v_cndmask_b32_e32 v0, v216, v36, vcc
	v_lshlrev_b32_e32 v0, 2, v0
	ds_bpermute_b32 v36, v0, v35
	ds_bpermute_b32 v0, v0, v34
	v_mov_b32_e32 v51, v65
	v_mov_b32_e32 v50, v65
	v_mov_b32_e32 v49, v65
	s_waitcnt lgkmcnt(1)
	v_or_b32_e32 v35, v36, v35
	s_waitcnt lgkmcnt(0)
	v_or_b32_e32 v0, v0, v34
	v_readfirstlane_b32 s0, v35
	v_readfirstlane_b32 s1, v0
	s_cmp_eq_u64 s[0:1], 0
	s_ff1_i32_b64 s30, s[0:1]
	s_cselect_b64 s[40:41], -1, 0
	s_cmp_lt_u32 s51, s30
	s_cselect_b64 s[42:43], -1, 0
	s_or_b64 s[38:39], s[38:39], s[40:41]
	s_or_b64 s[38:39], s[38:39], s[42:43]
	s_andn2_b64 vcc, exec, s[38:39]
	v_mov_b32_e32 v48, v65
	v_mov_b32_e32 v47, v65
	v_mov_b32_e32 v46, v65
	v_mov_b32_e32 v45, v65
	v_mov_b32_e32 v44, v65
	v_mov_b32_e32 v43, v65
	v_mov_b32_e32 v42, v65
	v_mov_b32_e32 v41, v65
	v_mov_b32_e32 v40, v65
	v_mov_b32_e32 v39, v65
	v_mov_b32_e32 v38, v65
	v_mov_b32_e32 v37, v65
	v_mov_b32_e32 v36, v65
	v_mov_b32_e32 v35, v65
	v_mov_b32_e32 v34, v65
	v_mov_b32_e32 v161, v65
	s_cbranch_vccz .LBB0_694
	v_readlane_b32 s14, v254, 34
	v_ashrrev_i32_e32 v131, 3, v66
	v_readlane_b32 s15, v254, 35
	v_lshlrev_b32_e32 v40, 4, v66
	v_lshl_add_u32 v0, s30, 6, v131
	v_mov_b64_e32 v[34:35], s[14:15]
	v_mad_i64_i32 v[34:35], s[38:39], v0, s80, v[34:35]
	v_and_b32_e32 v0, 0x70, v40
	v_lshl_add_u64 v[34:35], v[34:35], 0, v[0:1]
	s_mov_b32 s38, 0x38000
	v_lshlrev_b32_e32 v36, 3, v66
	v_add_co_u32_e32 v38, vcc, s38, v34
	s_lshl_b64 s[38:39], s[30:31], 13
	v_readlane_b32 s12, v254, 32
	v_readlane_b32 s13, v254, 33
	s_add_u32 s38, s12, s38
	v_ashrrev_i32_e32 v37, 31, v36
	v_addc_co_u32_e32 v39, vcc, 0, v35, vcc
	global_load_dwordx4 v[82:85], v[34:35], off offset:3840
	global_load_dwordx4 v[86:89], v[38:39], off offset:3840
	s_addc_u32 s39, s13, s39
	v_lshlrev_b64 v[34:35], 1, v[36:37]
	v_lshl_add_u64 v[36:37], s[38:39], 0, v[34:35]
	v_add_co_u32_e32 v38, vcc, s97, v36
	s_movk_i32 s16, 0x70
	s_nop 0
	v_addc_co_u32_e32 v39, vcc, 0, v37, vcc
	global_load_dwordx4 v[90:93], v[36:37], off
	global_load_dwordx4 v[94:97], v[38:39], off
	v_lshlrev_b32_e32 v38, 7, v131
	v_xor_b32_e32 v39, v40, v66
	v_and_or_b32 v139, v39, s16, v38
	v_lshlrev_b32_e32 v38, 6, v66
	v_bfe_u32 v37, v66, 5, 1
	v_and_b32_e32 v38, 64, v38
	v_and_b32_e32 v39, 0xfffff80, v66
	v_bfe_u32 v41, v66, 1, 6
	v_lshl_add_u64 v[134:135], s[14:15], 0, v[0:1]
	v_lshlrev_b32_e32 v0, 7, v66
	v_lshrrev_b32_e32 v40, 1, v66
	v_or3_b32 v38, v39, v38, v41
	v_and_b32_e32 v141, 0xf80, v0
	v_lshlrev_b32_e32 v0, 2, v37
	v_lshlrev_b32_e32 v140, 4, v66
	v_bfe_u32 v38, v66, 1, 3
	v_or_b32_e32 v142, 0x186a0, v0
	v_or_b32_e32 v143, 0x186a1, v0
	v_or_b32_e32 v144, 0x186a2, v0
	v_or_b32_e32 v145, 0x186a3, v0
	v_or_b32_e32 v146, 0x186a8, v0
	v_or_b32_e32 v147, 0x186a9, v0
	v_or_b32_e32 v148, 0x186aa, v0
	v_or_b32_e32 v149, 0x186ab, v0
	v_or_b32_e32 v150, 0x186b0, v0
	v_or_b32_e32 v151, 0x186b1, v0
	v_or_b32_e32 v152, 0x186b2, v0
	v_or_b32_e32 v153, 0x186b3, v0
	v_or_b32_e32 v162, 0x186b8, v0
	v_or_b32_e32 v163, 0x186b9, v0
	v_or_b32_e32 v164, 0x186ba, v0
	v_or_b32_e32 v165, 0x186bb, v0
	v_bitop3_b32 v0, v37, v40, 7 bitop3:0x78
	v_lshlrev_b32_e32 v166, 4, v0
	v_bitop3_b32 v0, v37, v38, 2 bitop3:0x36
	v_lshlrev_b32_e32 v172, 4, v0
	v_bitop3_b32 v0, v37, v38, 4 bitop3:0x36
	v_and_b32_e32 v36, 63, v66
	v_lshlrev_b32_e32 v173, 4, v0
	v_bitop3_b32 v0, v37, v38, 6 bitop3:0x36
	v_mov_b32_e32 v161, 0
	s_mov_b32 s52, 0
	v_lshl_add_u64 v[136:137], s[12:13], 0, v[34:35]
	v_lshlrev_b32_e32 v174, 4, v0
	v_lshlrev_b32_e32 v175, 4, v36
	v_mov_b32_e32 v176, 0xc61c4000
	v_mov_b32_e32 v34, 0
	v_mov_b32_e32 v35, v161
	v_mov_b32_e32 v36, v161
	v_mov_b32_e32 v37, v161
	v_mov_b32_e32 v38, v161
	v_mov_b32_e32 v39, v161
	v_mov_b32_e32 v40, v161
	v_mov_b32_e32 v41, v161
	v_mov_b32_e32 v42, v161
	v_mov_b32_e32 v43, v161
	v_mov_b32_e32 v44, v161
	v_mov_b32_e32 v45, v161
	v_mov_b32_e32 v46, v161
	v_mov_b32_e32 v47, v161
	v_mov_b32_e32 v48, v161
	v_mov_b32_e32 v49, v161
	v_mov_b32_e32 v50, v161
	v_mov_b32_e32 v51, v161
	v_mov_b32_e32 v52, v161
	v_mov_b32_e32 v53, v161
	v_mov_b32_e32 v54, v161
	v_mov_b32_e32 v55, v161
	v_mov_b32_e32 v56, v161
	v_mov_b32_e32 v57, v161
	v_mov_b32_e32 v58, v161
	v_mov_b32_e32 v59, v161
	v_mov_b32_e32 v60, v161
	v_mov_b32_e32 v61, v161
	v_mov_b32_e32 v62, v161
	v_mov_b32_e32 v63, v161
	v_mov_b32_e32 v64, v161
	v_mov_b32_e32 v65, v161

.LBB0_694:
	v_mov_b32_e32 v98, v199
	v_mov_b32_e32 v81, 0
	s_cmp_lt_i32 s44, 0
	v_mov_b32_e32 v80, 0
	v_mov_b32_e32 v79, 0
	v_mov_b32_e32 v78, 0
	v_mov_b32_e32 v77, 0
	v_mov_b32_e32 v76, 0
	v_mov_b32_e32 v75, 0
	v_mov_b32_e32 v74, 0
	v_mov_b32_e32 v73, 0
	v_mov_b32_e32 v72, 0
	v_mov_b32_e32 v71, 0
	v_mov_b32_e32 v70, 0
	v_mov_b32_e32 v69, 0
	v_mov_b32_e32 v68, 0
	v_mov_b32_e32 v67, 0
	v_mov_b32_e32 v66, 0
	s_waitcnt vmcnt(0)
	v_mov_b32_e32 v97, 0
	v_mov_b32_e32 v96, 0
	v_mov_b32_e32 v95, 0
	v_mov_b32_e32 v94, 0
	v_mov_b32_e32 v93, 0
	v_mov_b32_e32 v92, 0
	v_mov_b32_e32 v91, 0
	v_mov_b32_e32 v90, 0
	v_mov_b32_e32 v89, 0
	v_mov_b32_e32 v88, 0
	v_mov_b32_e32 v87, 0
	v_mov_b32_e32 v86, 0
	v_mov_b32_e32 v85, 0
	v_mov_b32_e32 v84, 0
	v_mov_b32_e32 v83, 0
	v_mov_b32_e32 v82, 0
	v_mov_b32_e32 v172, 0
	s_cbranch_scc1 .LBB0_651
	s_max_i32 s30, s44, 16
	s_add_i32 s30, s30, -16
	s_add_u32 s0, s34, s45
	s_addc_u32 s1, s35, 0
	s_mulk_i32 s1, 0x1c00
	s_mul_hi_u32 s38, s0, 0x1c00
	s_add_i32 s38, s38, s1
	s_mulk_i32 s0, 0x1c00
	v_ashrrev_i32_e32 v70, 3, v98
	s_add_u32 s0, s66, s0
	s_movk_i32 s14, 0xe00
	v_lshlrev_b32_e32 v68, 3, v98
	s_addc_u32 s1, s67, s38
	v_mad_i64_i32 v[162:163], s[40:41], v70, s14, 0
	v_and_b32_e32 v100, 56, v68
	v_lshl_add_u64 v[66:67], v[162:163], 1, s[0:1]
	v_lshlrev_b32_e32 v0, 1, v100
	s_mov_b32 s45, s31
	v_lshl_add_u64 v[66:67], v[66:67], 0, v[0:1]
	s_lshl_b64 s[38:39], s[44:45], 12
	v_readlane_b32 s12, v254, 36
	v_add_co_u32_e32 v66, vcc, s97, v66
	v_readlane_b32 s13, v254, 37
	s_add_u32 s38, s12, s38
	v_addc_co_u32_e32 v67, vcc, 0, v67, vcc
	v_ashrrev_i32_e32 v69, 31, v68
	s_addc_u32 s39, s13, s39
	global_load_dwordx4 v[130:133], v[66:67], off
	v_lshlrev_b64 v[66:67], 1, v[68:69]
	v_lshl_add_u64 v[68:69], s[38:39], 0, v[66:67]
	global_load_dwordx4 v[134:137], v[68:69], off
	v_lshlrev_b32_e32 v69, 4, v98
	s_movk_i32 s0, 0x70
	v_bitop3_b32 v174, v69, s0, v98 bitop3:0x48
	v_lshlrev_b32_e32 v69, 6, v98
	v_lshlrev_b32_e32 v173, 7, v70
	v_and_b32_e32 v69, 64, v69
	v_and_b32_e32 v70, 0xfffff80, v98
	v_bfe_u32 v72, v98, 1, 6
	v_bfe_u32 v68, v98, 5, 1
	v_lshrrev_b32_e32 v71, 1, v98
	v_or3_b32 v69, v70, v69, v72
	v_lshlrev_b32_e32 v175, 4, v98
	v_bfe_u32 v69, v98, 1, 3
	v_bitop3_b32 v71, v68, v71, 7 bitop3:0x78
	v_lshlrev_b32_e32 v70, 7, v98
	v_lshlrev_b32_e32 v177, 4, v71
	v_bitop3_b32 v71, v68, v69, 2 bitop3:0x36
	v_and_b32_e32 v0, 63, v98
	v_and_b32_e32 v176, 0xf80, v70
	v_lshlrev_b32_e32 v70, 2, v68
	v_lshlrev_b32_e32 v178, 4, v71
	v_bitop3_b32 v71, v68, v69, 4 bitop3:0x36
	v_bitop3_b32 v68, v68, v69, 6 bitop3:0x36
	s_mov_b32 s38, 0
	v_lshlrev_b32_e32 v179, 4, v71
	v_lshlrev_b32_e32 v180, 4, v68
	v_lshlrev_b32_e32 v181, 4, v0
	v_lshl_add_u64 v[164:165], s[12:13], 0, v[66:67]
	v_sub_u32_e32 v182, v70, v138
	v_or_b32_e32 v183, 0xfffffe00, v138
	v_mov_b32_e32 v82, v1
	v_mov_b32_e32 v83, v1
	v_mov_b32_e32 v84, v1
	v_mov_b32_e32 v85, v1
	v_mov_b32_e32 v86, v1
	v_mov_b32_e32 v87, v1
	v_mov_b32_e32 v88, v1
	v_mov_b32_e32 v89, v1
	v_mov_b32_e32 v90, v1
	v_mov_b32_e32 v91, v1
	v_mov_b32_e32 v92, v1
	v_mov_b32_e32 v93, v1
	v_mov_b32_e32 v94, v1
	v_mov_b32_e32 v95, v1
	v_mov_b32_e32 v96, v1
	v_mov_b32_e32 v97, v1
	v_mov_b32_e32 v66, v1
	v_mov_b32_e32 v67, v1
	v_mov_b32_e32 v68, v1
	v_mov_b32_e32 v69, v1
	v_mov_b32_e32 v70, v1
	v_mov_b32_e32 v71, v1
	v_mov_b32_e32 v72, v1
	v_mov_b32_e32 v73, v1
	v_mov_b32_e32 v74, v1
	v_mov_b32_e32 v75, v1
	v_mov_b32_e32 v76, v1
	v_mov_b32_e32 v77, v1
	v_mov_b32_e32 v78, v1
	v_mov_b32_e32 v79, v1
	v_mov_b32_e32 v80, v1
	v_mov_b32_e32 v81, v1
	v_mov_b32_e32 v166, 0xc61c4000
	v_mov_b32_e32 v172, 0
	v_lshlrev_b32_e32 v0, 1, v100
	s_branch .LBB0_697

.LBB0_705:
	s_add_i32 s39, s40, 0x180
	s_lshr_b32 s43, s42, 2
	s_lshl_b32 s40, s44, 5
	s_add_i32 s40, s43, s40
	s_add_i32 s45, s40, 0xffffff80
	v_lshlrev_b32_e32 v36, 3, v34
	v_lshlrev_b32_e32 v30, 16, v0
	v_and_b32_e32 v31, 0xffff0000, v0
	v_or_b32_e32 v0, s45, v159
	v_or_b32_e32 v36, s39, v36
	s_ashr_i32 s39, s38, 31
	s_ashr_i32 s40, s45, 5
	v_lshl_add_u32 v38, v0, 2, v158
	s_ashr_i32 s41, s40, 31
	s_lshl_b64 s[38:39], s[38:39], 19
	v_ashrrev_i32_e32 v39, 31, v38
	s_lshl_b64 s[40:41], s[40:41], 12
	v_lshl_add_u64 v[170:171], v[160:161], 0, s[38:39]
	v_lshl_add_u64 v[38:39], s[0:1], 0, v[38:39]
	v_mov_b64_e32 v[42:43], s[66:67]
	v_lshl_add_u64 v[40:41], v[170:171], 0, s[40:41]
	v_mad_u64_u32 v[42:43], s[40:41], v38, s80, v[42:43]
	v_mov_b32_e32 v37, v1
	v_and_b32_e32 v35, 63, v2
	v_mad_i32_i24 v43, v39, s80, v43
	v_lshlrev_b64 v[36:37], 1, v[36:37]
	v_lshlrev_b32_e32 v0, 5, v35
	v_lshl_add_u64 v[38:39], v[42:43], 0, v[36:37]
	v_lshl_add_u64 v[40:41], v[40:41], 0, v[0:1]
	v_and_b32_e32 v238, 63, v199
	v_lshrrev_b32_e32 v239, 3, v238
	v_and_b32_e32 v240, 31, v238
	v_sub_u32_e32 v224, v239, v240
	v_add_u32_e32 v225, 8, v224
	v_add_u32_e32 v226, 16, v224
	v_add_u32_e32 v227, 24, v224
	v_lshrrev_b32_e32 v241, 5, v238
	v_and_b32_e32 v242, 7, v238
	v_lshrrev_b32_e32 v243, 4, v238
	v_xor_b32_e32 v228, v242, v243
	v_xor_b32_e32 v229, 4, v228
	v_sub_u32_e32 v228, v228, v241
	v_sub_u32_e32 v229, v229, v241
	v_lshlrev_b32_e32 v228, 4, v228
	v_lshlrev_b32_e32 v229, 4, v229
	v_lshrrev_b32_e32 v250, 6, v199
	v_lshlrev_b32_e32 v250, 13, v250
	v_bfe_u32 v251, v238, 1, 3
	v_xor_b32_e32 v251, v251, v241
	v_lshlrev_b32_e32 v251, 4, v251
	v_lshl_add_u32 v251, v240, 7, v251
	v_add_u32_e32 v234, v250, v251
	v_xor_b32_e32 v235, 0x20, v234
	v_xor_b32_e32 v236, 0x40, v234
	v_xor_b32_e32 v237, 0x60, v234
	v_readfirstlane_b32 s98, v250
	s_mov_b32 s99, 0x7000
	s_add_u32 m0, s98, 0x0
	v_mad_i64_i32 v[232:233], s[100:101], v224, s99, v[38:39]
	v_add_u32_e32 v232, v228, v232
	global_load_lds_dwordx4 v[232:233], off
	s_add_u32 m0, s98, 0x400
	v_mad_i64_i32 v[232:233], s[100:101], v225, s99, v[38:39]
	v_add_u32_e32 v232, v229, v232
	global_load_lds_dwordx4 v[232:233], off
	s_add_u32 m0, s98, 0x800
	v_mad_i64_i32 v[232:233], s[100:101], v226, s99, v[38:39]
	v_add_u32_e32 v232, v228, v232
	global_load_lds_dwordx4 v[232:233], off
	s_add_u32 m0, s98, 0xc00
	v_mad_i64_i32 v[232:233], s[100:101], v227, s99, v[38:39]
	v_add_u32_e32 v232, v229, v232
	global_load_lds_dwordx4 v[232:233], off
	v_and_b32_e32 v230, 63, v199
	v_lshlrev_b32_e32 v230, 4, v230
	v_sub_u32_e32 v230, 0, v230
	v_ashrrev_i32_e32 v231, 31, v230
	v_lshl_add_u64 v[230:231], v[40:41], 0, v[230:231]
	global_load_dwordx4 v[110:113], v[230:231], off
	global_load_dwordx4 v[106:109], v[230:231], off offset:1024
	global_load_dwordx4 v[102:105], v[230:231], off offset:2048
	global_load_dwordx4 v[98:101], v[230:231], off offset:3072
	v_readlane_b32 s12, v253, 2
	v_lshlrev_b32_e32 v167, 2, v34
	v_readlane_b32 s13, v253, 3
	v_readlane_b32 s23, v253, 13
	v_readlane_b32 s24, v253, 14
	v_readlane_b32 s25, v253, 15
	v_readlane_b32 s26, v253, 16
	v_readlane_b32 s27, v253, 17
	s_add_u32 s45, s12, s38
	v_lshlrev_b32_e32 v2, 16, v4
	v_and_b32_e32 v3, 0xffff0000, v4
	v_lshlrev_b32_e32 v4, 16, v5
	v_and_b32_e32 v5, 0xffff0000, v5
	v_lshlrev_b32_e32 v6, 16, v8
	v_and_b32_e32 v7, 0xffff0000, v8
	v_lshlrev_b32_e32 v8, 16, v9
	v_and_b32_e32 v9, 0xffff0000, v9
	v_lshlrev_b32_e32 v10, 16, v12
	v_and_b32_e32 v11, 0xffff0000, v12
	v_lshlrev_b32_e32 v12, 16, v13
	v_and_b32_e32 v13, 0xffff0000, v13
	v_lshlrev_b32_e32 v14, 16, v16
	v_and_b32_e32 v15, 0xffff0000, v16
	v_lshlrev_b32_e32 v16, 16, v17
	v_and_b32_e32 v17, 0xffff0000, v17
	v_lshlrev_b32_e32 v18, 16, v20
	v_and_b32_e32 v19, 0xffff0000, v20
	v_lshlrev_b32_e32 v20, 16, v21
	v_and_b32_e32 v21, 0xffff0000, v21
	v_lshlrev_b32_e32 v22, 16, v24
	v_and_b32_e32 v23, 0xffff0000, v24
	v_lshlrev_b32_e32 v24, 16, v25
	v_and_b32_e32 v25, 0xffff0000, v25
	v_lshlrev_b32_e32 v26, 16, v28
	v_and_b32_e32 v27, 0xffff0000, v28
	v_lshlrev_b32_e32 v28, 16, v29
	v_and_b32_e32 v29, 0xffff0000, v29
	v_lshlrev_b32_e32 v32, 16, v33
	v_and_b32_e32 v33, 0xffff0000, v33
	v_lshlrev_b32_e32 v172, 4, v35
	v_or_b32_e32 v173, 0x80, v167
	v_lshl_add_u64 v[174:175], s[66:67], 0, v[36:37]
	v_or_b32_e32 v178, s43, v159
	s_addc_u32 s46, s13, s39
	s_mov_b32 s23, 0x800000
	s_movk_i32 s24, 0xf00
	s_movk_i32 s25, 0x104
	s_mov_b64 s[26:27], 0x400c0
	v_readlane_b32 s14, v253, 4
	v_readlane_b32 s15, v253, 5
	v_readlane_b32 s16, v253, 6
	v_readlane_b32 s17, v253, 7
	v_readlane_b32 s18, v253, 8
	v_readlane_b32 s19, v253, 9
	v_readlane_b32 s20, v253, 10
	v_readlane_b32 s21, v253, 11
	v_readlane_b32 s22, v253, 12
	s_branch .LBB0_709

.LBB0_713:
	s_cmp_gt_i32 s47, -1
	s_cselect_b64 s[38:39], -1, 0
	s_cmp_lt_i32 s47, 0
	s_cselect_b32 s41, s44, s47
	s_cmp_lt_i32 s41, 5
	s_cselect_b64 vcc, -1, 0
	s_movk_i32 s99, 0x1c00
	s_cselect_b32 s99, 0x7000, s99
	s_and_b64 s[48:49], vcc, exec
	s_cselect_b32 s48, 0xffffff80, s83
	s_cselect_b32 s49, s43, s42
	s_lshl_b32 s41, s41, 5
	s_add_i32 s41, s48, s41
	v_mov_b32_e32 v0, s46
	s_add_i32 s41, s41, s49
	v_cndmask_b32_e32 v35, v0, v171, vcc
	v_or_b32_e32 v0, s41, v159
	v_lshl_add_u32 v36, v0, 2, v158
	s_ashr_i32 s48, s41, 5
	v_cndmask_b32_e32 v36, v0, v36, vcc
	s_ashr_i32 s49, s48, 31
	v_mov_b32_e32 v34, s45
	v_ashrrev_i32_e32 v37, 31, v36
	v_cndmask_b32_e32 v34, v34, v170, vcc
	s_lshl_b64 s[48:49], s[48:49], 12
	v_lshl_add_u64 v[52:53], s[0:1], 0, v[36:37]
	v_lshl_add_u64 v[34:35], v[34:35], 0, s[48:49]
	v_mad_u64_u32 v[54:55], s[48:49], v52, s80, v[174:175]
	v_lshlrev_b32_e32 v0, 1, v172
	v_mad_i32_i24 v55, v53, s80, v55
	v_lshl_add_u64 v[50:51], v[34:35], 0, v[0:1]
	s_add_u32 m0, s98, 0x1000
	v_mad_i64_i32 v[232:233], s[100:101], v224, s99, v[54:55]
	v_add_u32_e32 v232, v228, v232
	global_load_lds_dwordx4 v[232:233], off
	s_add_u32 m0, s98, 0x1400
	v_mad_i64_i32 v[232:233], s[100:101], v225, s99, v[54:55]
	v_add_u32_e32 v232, v229, v232
	global_load_lds_dwordx4 v[232:233], off
	s_add_u32 m0, s98, 0x1800
	v_mad_i64_i32 v[232:233], s[100:101], v226, s99, v[54:55]
	v_add_u32_e32 v232, v228, v232
	global_load_lds_dwordx4 v[232:233], off
	s_add_u32 m0, s98, 0x1c00
	v_mad_i64_i32 v[232:233], s[100:101], v227, s99, v[54:55]
	v_add_u32_e32 v232, v229, v232
	global_load_lds_dwordx4 v[232:233], off
	v_and_b32_e32 v230, 63, v199
	v_lshlrev_b32_e32 v230, 4, v230
	v_sub_u32_e32 v230, 0, v230
	v_ashrrev_i32_e32 v231, 31, v230
	v_lshl_add_u64 v[230:231], v[50:51], 0, v[230:231]
	global_load_dwordx4 v[130:133], v[230:231], off
	global_load_dwordx4 v[122:125], v[230:231], off offset:1024
	global_load_dwordx4 v[118:121], v[230:231], off offset:2048
	global_load_dwordx4 v[114:117], v[230:231], off offset:3072
	s_waitcnt vmcnt(12)
	ds_read_b128 v[142:145], v234
	ds_read_b128 v[134:137], v235
	ds_read_b128 v[126:129], v236
	ds_read_b128 v[138:141], v237
	s_waitcnt lgkmcnt(3)
	v_mfma_f32_32x32x16_bf16 v[34:49], v[142:145], v[82:85], 0
	s_cmp_lt_u32 s44, 5
	s_cselect_b64 vcc, -1, 0
	s_and_b64 s[48:49], vcc, exec
	v_cndmask_b32_e32 v50, v166, v178, vcc
	s_cselect_b32 s41, 0x80, s58
	s_cselect_b32 s44, s43, s42
	v_add_u32_e32 v50, s41, v50
	s_waitcnt lgkmcnt(2)
	v_mfma_f32_32x32x16_bf16 v[34:49], v[134:137], v[86:89], v[34:49]
	s_add_i32 s40, s40, s44
	v_subrev_u32_e32 v50, s40, v50
	v_add_u32_e32 v51, 0xffffff7f, v50
	v_cmp_gt_u32_e32 vcc, s2, v51
	s_waitcnt lgkmcnt(1)
	v_mfma_f32_32x32x16_bf16 v[34:49], v[126:129], v[90:93], v[34:49]
	s_waitcnt lgkmcnt(0)
	v_mfma_f32_32x32x16_bf16 v[34:49], v[138:141], v[94:97], v[34:49]
	s_cbranch_vccz .LBB0_715
	v_sub_u32_e32 v50, v173, v50
	v_cmp_gt_u32_e32 vcc, s3, v50
	v_add_u32_e32 v51, 0xffffff80, v50
	s_nop 7
	v_cndmask_b32_e32 v34, v212, v34, vcc
	v_cmp_lt_u32_e32 vcc, s8, v51
	v_add_u32_e32 v51, 0xffffff81, v50
	s_nop 0
	v_cndmask_b32_e32 v35, v212, v35, vcc
	v_cmp_lt_u32_e32 vcc, s8, v51
	v_add_u32_e32 v51, 0xffffff82, v50
	s_nop 0
	v_cndmask_b32_e32 v36, v212, v36, vcc
	v_cmp_lt_u32_e32 vcc, s8, v51
	v_add_u32_e32 v51, 0xffffff87, v50
	s_nop 0
	v_cndmask_b32_e32 v37, v212, v37, vcc
	v_cmp_lt_u32_e32 vcc, s8, v51
	v_add_u32_e32 v51, 0xffffff88, v50
	s_nop 0
	v_cndmask_b32_e32 v38, v212, v38, vcc
	v_cmp_lt_u32_e32 vcc, s8, v51
	v_add_u32_e32 v51, 0xffffff89, v50
	s_nop 0
	v_cndmask_b32_e32 v39, v212, v39, vcc
	v_cmp_lt_u32_e32 vcc, s8, v51
	v_add_u32_e32 v51, 0xffffff8a, v50
	s_nop 0
	v_cndmask_b32_e32 v40, v212, v40, vcc
	v_cmp_lt_u32_e32 vcc, s8, v51
	v_add_u32_e32 v51, 0xffffff8f, v50
	s_nop 0
	v_cndmask_b32_e32 v41, v212, v41, vcc
	v_cmp_lt_u32_e32 vcc, s8, v51
	v_add_u32_e32 v51, 0xffffff90, v50
	s_nop 0
	v_cndmask_b32_e32 v42, v212, v42, vcc
	v_cmp_lt_u32_e32 vcc, s8, v51
	v_add_u32_e32 v51, 0xffffff91, v50
	s_nop 0
	v_cndmask_b32_e32 v43, v212, v43, vcc
	v_cmp_lt_u32_e32 vcc, s8, v51
	v_add_u32_e32 v51, 0xffffff92, v50
	s_nop 0
	v_cndmask_b32_e32 v44, v212, v44, vcc
	v_cmp_lt_u32_e32 vcc, s8, v51
	v_add_u32_e32 v51, 0xffffff97, v50
	s_nop 0
	v_cndmask_b32_e32 v45, v212, v45, vcc
	v_cmp_lt_u32_e32 vcc, s8, v51
	v_add_u32_e32 v51, 0xffffff98, v50
	s_nop 0
	v_cndmask_b32_e32 v46, v212, v46, vcc
	v_cmp_lt_u32_e32 vcc, s8, v51
	v_add_u32_e32 v51, 0xffffff99, v50
	v_add_u32_e32 v50, 0xffffff9a, v50
	v_cndmask_b32_e32 v47, v212, v47, vcc
	v_cmp_lt_u32_e32 vcc, s8, v51
	s_nop 1
	v_cndmask_b32_e32 v48, v212, v48, vcc
	v_cmp_lt_u32_e32 vcc, s8, v50
	s_nop 1
	v_cndmask_b32_e32 v49, v212, v49, vcc

.LBB0_722:
	s_cmp_lt_i32 s44, 0
	s_cselect_b64 s[38:39], -1, 0
	s_cmp_gt_i32 s44, -1
	s_cselect_b32 s41, s44, s47
	s_cmp_lt_i32 s41, 5
	s_cselect_b64 vcc, -1, 0
	s_movk_i32 s99, 0x1c00
	s_cselect_b32 s99, 0x7000, s99
	s_and_b64 s[48:49], vcc, exec
	s_cselect_b32 s48, 0xffffff80, s83
	s_cselect_b32 s49, s43, s42
	s_lshl_b32 s41, s41, 5
	s_add_i32 s41, s48, s41
	s_add_i32 s41, s41, s49
	v_or_b32_e32 v4, s41, v159
	v_lshl_add_u32 v5, v4, 2, v158
	v_mov_b32_e32 v2, s46
	s_ashr_i32 s48, s41, 5
	v_cndmask_b32_e32 v4, v4, v5, vcc
	v_cndmask_b32_e32 v3, v2, v171, vcc
	s_ashr_i32 s49, s48, 31
	v_mov_b32_e32 v2, s45
	v_ashrrev_i32_e32 v5, 31, v4
	v_cndmask_b32_e32 v2, v2, v170, vcc
	s_lshl_b64 s[48:49], s[48:49], 12
	v_lshl_add_u64 v[4:5], s[0:1], 0, v[4:5]
	v_lshl_add_u64 v[2:3], v[2:3], 0, s[48:49]
	v_mad_u64_u32 v[6:7], s[48:49], v4, s80, v[174:175]
	v_mad_i32_i24 v7, v5, s80, v7
	v_lshl_add_u64 v[2:3], v[2:3], 0, v[0:1]
	s_add_u32 m0, s98, 0x0
	v_mad_i64_i32 v[232:233], s[100:101], v224, s99, v[6:7]
	v_add_u32_e32 v232, v228, v232
	global_load_lds_dwordx4 v[232:233], off
	s_add_u32 m0, s98, 0x400
	v_mad_i64_i32 v[232:233], s[100:101], v225, s99, v[6:7]
	v_add_u32_e32 v232, v229, v232
	global_load_lds_dwordx4 v[232:233], off
	s_add_u32 m0, s98, 0x800
	v_mad_i64_i32 v[232:233], s[100:101], v226, s99, v[6:7]
	v_add_u32_e32 v232, v228, v232
	global_load_lds_dwordx4 v[232:233], off
	s_add_u32 m0, s98, 0xc00
	v_mad_i64_i32 v[232:233], s[100:101], v227, s99, v[6:7]
	v_add_u32_e32 v232, v229, v232
	global_load_lds_dwordx4 v[232:233], off
	v_and_b32_e32 v230, 63, v199
	v_lshlrev_b32_e32 v230, 4, v230
	v_sub_u32_e32 v230, 0, v230
	v_ashrrev_i32_e32 v231, 31, v230
	v_lshl_add_u64 v[230:231], v[2:3], 0, v[230:231]
	global_load_dwordx4 v[110:113], v[230:231], off
	global_load_dwordx4 v[106:109], v[230:231], off offset:1024
	global_load_dwordx4 v[102:105], v[230:231], off offset:2048
	global_load_dwordx4 v[98:101], v[230:231], off offset:3072
	s_waitcnt vmcnt(12)
	ds_read_b128 v[66:69], v234 offset:4096
	ds_read_b128 v[154:157], v235 offset:4096
	ds_read_b128 v[150:153], v236 offset:4096
	ds_read_b128 v[146:149], v237 offset:4096
	s_waitcnt lgkmcnt(3)
	v_mfma_f32_32x32x16_bf16 v[66:81], v[66:69], v[82:85], 0
	s_cmp_lt_u32 s47, 5
	s_cselect_b64 vcc, -1, 0
	s_and_b64 s[48:49], vcc, exec
	v_cndmask_b32_e32 v0, v166, v178, vcc
	s_cselect_b32 s41, 0x80, s58
	s_cselect_b32 s47, s43, s42
	v_add_u32_e32 v0, s41, v0
	s_waitcnt lgkmcnt(2)
	v_mfma_f32_32x32x16_bf16 v[66:81], v[154:157], v[86:89], v[66:81]
	s_add_i32 s40, s40, s47
	v_subrev_u32_e32 v0, s40, v0
	v_add_u32_e32 v2, 0xffffff7f, v0
	v_cmp_gt_u32_e32 vcc, s2, v2
	s_waitcnt lgkmcnt(1)
	v_mfma_f32_32x32x16_bf16 v[66:81], v[150:153], v[90:93], v[66:81]
	s_waitcnt lgkmcnt(0)
	v_mfma_f32_32x32x16_bf16 v[66:81], v[146:149], v[94:97], v[66:81]
	s_cbranch_vccz .LBB0_724
	v_sub_u32_e32 v0, v173, v0
	v_cmp_gt_u32_e32 vcc, s3, v0
	v_add_u32_e32 v2, 0xffffff80, v0
	s_nop 7
	v_cndmask_b32_e32 v66, v212, v66, vcc
	v_cmp_lt_u32_e32 vcc, s8, v2
	v_add_u32_e32 v2, 0xffffff81, v0
	s_nop 0
	v_cndmask_b32_e32 v67, v212, v67, vcc
	v_cmp_lt_u32_e32 vcc, s8, v2
	v_add_u32_e32 v2, 0xffffff82, v0
	s_nop 0
	v_cndmask_b32_e32 v68, v212, v68, vcc
	v_cmp_lt_u32_e32 vcc, s8, v2
	v_add_u32_e32 v2, 0xffffff87, v0
	s_nop 0
	v_cndmask_b32_e32 v69, v212, v69, vcc
	v_cmp_lt_u32_e32 vcc, s8, v2
	v_add_u32_e32 v2, 0xffffff88, v0
	s_nop 0
	v_cndmask_b32_e32 v70, v212, v70, vcc
	v_cmp_lt_u32_e32 vcc, s8, v2
	v_add_u32_e32 v2, 0xffffff89, v0
	s_nop 0
	v_cndmask_b32_e32 v71, v212, v71, vcc
	v_cmp_lt_u32_e32 vcc, s8, v2
	v_add_u32_e32 v2, 0xffffff8a, v0
	s_nop 0
	v_cndmask_b32_e32 v72, v212, v72, vcc
	v_cmp_lt_u32_e32 vcc, s8, v2
	v_add_u32_e32 v2, 0xffffff8f, v0
	s_nop 0
	v_cndmask_b32_e32 v73, v212, v73, vcc
	v_cmp_lt_u32_e32 vcc, s8, v2
	v_add_u32_e32 v2, 0xffffff90, v0
	s_nop 0
	v_cndmask_b32_e32 v74, v212, v74, vcc
	v_cmp_lt_u32_e32 vcc, s8, v2
	v_add_u32_e32 v2, 0xffffff91, v0
	s_nop 0
	v_cndmask_b32_e32 v75, v212, v75, vcc
	v_cmp_lt_u32_e32 vcc, s8, v2
	v_add_u32_e32 v2, 0xffffff92, v0
	s_nop 0
	v_cndmask_b32_e32 v76, v212, v76, vcc
	v_cmp_lt_u32_e32 vcc, s8, v2
	v_add_u32_e32 v2, 0xffffff97, v0
	s_nop 0
	v_cndmask_b32_e32 v77, v212, v77, vcc
	v_cmp_lt_u32_e32 vcc, s8, v2
	v_add_u32_e32 v2, 0xffffff98, v0
	s_nop 0
	v_cndmask_b32_e32 v78, v212, v78, vcc
	v_cmp_lt_u32_e32 vcc, s8, v2
	v_add_u32_e32 v2, 0xffffff99, v0
	v_add_u32_e32 v0, 0xffffff9a, v0
	v_cndmask_b32_e32 v79, v212, v79, vcc
	v_cmp_lt_u32_e32 vcc, s8, v2
	s_nop 1
	v_cndmask_b32_e32 v80, v212, v80, vcc
	v_cmp_lt_u32_e32 vcc, s8, v0
	s_nop 1
	v_cndmask_b32_e32 v81, v212, v81, vcc

.LBB0_759:
	s_or_b64 exec, exec, s[40:41]
	v_ashrrev_i32_e32 v165, 31, v164
	v_readlane_b32 s48, v252, 0
	v_ashrrev_i32_e32 v167, 31, v166
	v_lshlrev_b64 v[2:3], 17, v[164:165]
	v_readlane_b32 s49, v252, 1
	v_mov_b32_e32 v0, v199
	v_lshlrev_b64 v[4:5], 13, v[166:167]
	v_lshl_add_u64 v[2:3], s[48:49], 0, v[2:3]
	v_lshl_add_u64 v[2:3], v[2:3], 0, v[4:5]
	v_lshlrev_b32_e32 v4, 5, v192
	v_and_or_b32 v0, v0, 31, v4
	s_waitcnt vmcnt(0)
	v_add_u32_e32 v4, -1, v193
	v_min_i32_e32 v4, v0, v4
	v_ashrrev_i32_e32 v5, 31, v4
	v_lshl_add_u64 v[2:3], v[4:5], 1, v[2:3]
	v_ashrrev_i32_e32 v159, 31, v158
	v_readlane_b32 s12, v252, 8
	global_load_ushort v165, v[2:3], off
	v_lshlrev_b64 v[2:3], 13, v[158:159]
	v_readlane_b32 s18, v252, 14
	v_readlane_b32 s19, v252, 15
	v_mov_b32_e32 v163, v1
	v_mov_b32_e32 v0, v199
	v_lshl_add_u64 v[2:3], s[18:19], 0, v[2:3]
	v_lshl_add_u64 v[2:3], v[162:163], 1, v[2:3]
	global_load_ushort v200, v[2:3], off
	v_ashrrev_i32_e32 v2, 2, v158
	v_ashrrev_i32_e32 v3, 31, v2
	v_lshlrev_b64 v[174:175], 12, v[2:3]
	s_and_b64 s[0:1], exec, vcc
	v_lshl_add_u64 v[172:173], v[174:175], 0, v[162:163]
	s_movk_i32 s12, 0xe00
	s_or_b64 s[44:45], s[0:1], s[44:45]
	v_mad_u64_u32 v[2:3], s[0:1], v172, s12, 0
	v_lshrrev_b32_e32 v4, 2, v0
	v_mad_i32_i24 v3, v173, s12, v3
	v_and_b32_e32 v4, 8, v4
	v_and_b32_e32 v167, 3, v158
	v_and_b32_e32 v201, 31, v0
	v_and_b32_e32 v163, 63, v0
	v_cmp_lt_i32_e32 vcc, -1, v160
	v_mov_b32_e32 v183, 0xc61c4000
	v_mov_b32_e32 v71, 0
	v_lshl_add_u64 v[170:171], v[2:3], 1, s[66:67]
	v_lshlrev_b32_e32 v168, 1, v4
	v_mov_b32_e32 v49, 0
	v_mov_b32_e32 v48, 0
	v_mov_b32_e32 v47, 0
	v_mov_b32_e32 v46, 0
	v_mov_b32_e32 v45, 0
	v_mov_b32_e32 v44, 0
	v_mov_b32_e32 v43, 0
	v_mov_b32_e32 v42, 0
	v_mov_b32_e32 v41, 0
	v_mov_b32_e32 v40, 0
	v_mov_b32_e32 v39, 0
	v_mov_b32_e32 v38, 0
	v_mov_b32_e32 v37, 0
	v_mov_b32_e32 v36, 0
	v_mov_b32_e32 v35, 0
	v_mov_b32_e32 v34, 0
	v_mov_b32_e32 v65, 0
	v_mov_b32_e32 v64, 0
	v_mov_b32_e32 v63, 0
	v_mov_b32_e32 v62, 0
	v_mov_b32_e32 v61, 0
	v_mov_b32_e32 v60, 0
	v_mov_b32_e32 v59, 0
	v_mov_b32_e32 v58, 0
	v_mov_b32_e32 v57, 0
	v_mov_b32_e32 v56, 0
	v_mov_b32_e32 v55, 0
	v_mov_b32_e32 v54, 0
	v_mov_b32_e32 v53, 0
	v_mov_b32_e32 v52, 0
	v_mov_b32_e32 v51, 0
	v_mov_b32_e32 v50, 0
	v_readlane_b32 s50, v252, 2
	v_readlane_b32 s51, v252, 3
	v_readlane_b32 s52, v252, 4
	v_readlane_b32 s53, v252, 5
	v_readlane_b32 s54, v252, 6
	v_readlane_b32 s55, v252, 7
	v_readlane_b32 s13, v252, 9
	v_readlane_b32 s14, v252, 10
	v_readlane_b32 s15, v252, 11
	v_readlane_b32 s16, v252, 12
	v_readlane_b32 s17, v252, 13
	s_and_saveexec_b64 s[0:1], vcc
	s_cbranch_execz .LBB0_775
	v_readlane_b32 s12, v253, 2
	v_lshlrev_b64 v[2:3], 19, v[158:159]
	v_readlane_b32 s22, v253, 12
	v_readlane_b32 s23, v253, 13
	v_lshlrev_b32_e32 v0, 5, v163
	v_readlane_b32 s13, v253, 3
	v_lshl_add_u64 v[2:3], s[22:23], 0, v[2:3]
	v_lshl_add_u64 v[176:177], v[2:3], 0, v[0:1]
	v_lshlrev_b32_e32 v0, 7, v167
	v_lshl_add_u64 v[4:5], v[170:171], 0, v[0:1]
	v_mov_b32_e32 v169, v1
	v_lshl_add_u64 v[4:5], v[4:5], 0, v[168:169]
	s_mov_b64 s[12:13], 0x1300
	v_lshl_add_u64 v[6:7], v[4:5], 0, s[12:13]
	v_add_co_u32_e32 v4, vcc, s97, v4
	global_load_dwordx4 v[82:85], v[6:7], off offset:64
	global_load_dwordx4 v[86:89], v[6:7], off offset:32
	v_addc_co_u32_e32 v5, vcc, 0, v5, vcc
	global_load_dwordx4 v[90:93], v[6:7], off offset:96
	global_load_dwordx4 v[94:97], v[4:5], off offset:768
	v_or_b32_e32 v6, v0, v168
	v_lshlrev_b32_e32 v0, 8, v160
	v_lshl_add_u64 v[4:5], v[174:175], 0, v[0:1]
	v_mov_b64_e32 v[2:3], s[66:67]
	v_or_b32_e32 v0, v4, v201
	v_mad_u64_u32 v[2:3], s[40:41], v0, s80, v[2:3]
	v_lshlrev_b32_e32 v184, 3, v160
	v_mad_i32_i24 v3, v5, s80, v3
	v_add_u32_e32 v0, 0x1500, v6
	v_mov_b32_e32 v185, v1
	v_lshl_add_u64 v[2:3], v[2:3], 0, v[0:1]
	v_lshlrev_b64 v[4:5], 12, v[184:185]
	v_lshl_add_u64 v[4:5], v[176:177], 0, v[4:5]
	v_and_b32_e32 v238, 63, v199
	v_lshrrev_b32_e32 v239, 3, v238
	v_and_b32_e32 v240, 31, v238
	v_sub_u32_e32 v224, v239, v240
	v_add_u32_e32 v225, 8, v224
	v_add_u32_e32 v226, 16, v224
	v_add_u32_e32 v227, 24, v224
	v_lshrrev_b32_e32 v241, 5, v238
	v_and_b32_e32 v242, 7, v238
	v_lshrrev_b32_e32 v243, 4, v238
	v_xor_b32_e32 v228, v242, v243
	v_xor_b32_e32 v229, 4, v228
	v_sub_u32_e32 v228, v228, v241
	v_sub_u32_e32 v229, v229, v241
	v_lshlrev_b32_e32 v228, 4, v228
	v_lshlrev_b32_e32 v229, 4, v229
	v_lshrrev_b32_e32 v250, 6, v199
	v_lshlrev_b32_e32 v250, 13, v250
	v_bfe_u32 v251, v238, 1, 3
	v_xor_b32_e32 v251, v251, v241
	v_lshlrev_b32_e32 v251, 4, v251
	v_lshl_add_u32 v251, v240, 7, v251
	v_add_u32_e32 v234, v250, v251
	v_xor_b32_e32 v235, 0x20, v234
	v_xor_b32_e32 v236, 0x40, v234
	v_xor_b32_e32 v237, 0x60, v234
	v_readfirstlane_b32 s98, v250
	s_mov_b32 s99, 0x1c00
	s_add_u32 m0, s98, 0x0
	v_mad_i64_i32 v[232:233], s[100:101], v224, s99, v[2:3]
	v_add_u32_e32 v232, v228, v232
	global_load_lds_dwordx4 v[232:233], off
	s_add_u32 m0, s98, 0x400
	v_mad_i64_i32 v[232:233], s[100:101], v225, s99, v[2:3]
	v_add_u32_e32 v232, v229, v232
	global_load_lds_dwordx4 v[232:233], off
	s_add_u32 m0, s98, 0x800
	v_mad_i64_i32 v[232:233], s[100:101], v226, s99, v[2:3]
	v_add_u32_e32 v232, v228, v232
	global_load_lds_dwordx4 v[232:233], off
	s_add_u32 m0, s98, 0xc00
	v_mad_i64_i32 v[232:233], s[100:101], v227, s99, v[2:3]
	v_add_u32_e32 v232, v229, v232
	global_load_lds_dwordx4 v[232:233], off
	v_and_b32_e32 v230, 63, v199
	v_lshlrev_b32_e32 v230, 4, v230
	v_sub_u32_e32 v230, 0, v230
	v_ashrrev_i32_e32 v231, 31, v230
	v_lshl_add_u64 v[230:231], v[4:5], 0, v[230:231]
	global_load_dwordx4 v[110:113], v[230:231], off
	global_load_dwordx4 v[106:109], v[230:231], off offset:1024
	global_load_dwordx4 v[102:105], v[230:231], off offset:2048
	global_load_dwordx4 v[98:101], v[230:231], off offset:3072
	v_mov_b32_e32 v2, v1
	v_mov_b32_e32 v3, v1
	v_mov_b32_e32 v4, v1
	v_mov_b32_e32 v5, v1
	v_mov_b32_e32 v6, v1
	v_mov_b32_e32 v7, v1
	v_mov_b32_e32 v8, v1
	v_mov_b32_e32 v9, v1
	v_mov_b32_e32 v10, v1
	v_mov_b32_e32 v11, v1
	v_mov_b32_e32 v12, v1
	v_mov_b32_e32 v13, v1
	v_mov_b32_e32 v14, v1
	v_mov_b32_e32 v15, v1
	v_mov_b32_e32 v16, v1
	v_mov_b32_e32 v17, v1
	v_mov_b32_e32 v18, v1
	v_mov_b32_e32 v19, v1
	v_mov_b32_e32 v20, v1
	v_mov_b32_e32 v21, v1
	v_mov_b32_e32 v22, v1
	v_mov_b32_e32 v23, v1
	v_mov_b32_e32 v24, v1
	v_mov_b32_e32 v25, v1
	v_mov_b32_e32 v26, v1
	v_mov_b32_e32 v27, v1
	v_mov_b32_e32 v28, v1
	v_mov_b32_e32 v29, v1
	v_mov_b32_e32 v30, v1
	v_mov_b32_e32 v31, v1
	v_lshl_add_u64 v[178:179], s[66:67], 0, v[0:1]
	v_mov_b32_e32 v0, v1
	v_mov_b64_e32 v[32:33], v[30:31]
	v_or_b32_e32 v159, 7, v184
	v_or_b32_e32 v174, v174, v201
	v_mov_b32_e32 v183, 0xc61c4000
	v_mov_b32_e32 v71, 0
	s_mov_b64 s[46:47], 0
	v_mov_b64_e32 v[30:31], v[28:29]
	v_mov_b64_e32 v[28:29], v[26:27]
	v_mov_b64_e32 v[26:27], v[24:25]
	v_mov_b64_e32 v[24:25], v[22:23]
	v_mov_b64_e32 v[22:23], v[20:21]
	v_mov_b64_e32 v[20:21], v[18:19]
	v_mov_b64_e32 v[18:19], v[16:17]
	v_mov_b64_e32 v[16:17], v[14:15]
	v_mov_b64_e32 v[14:15], v[12:13]
	v_mov_b64_e32 v[12:13], v[10:11]
	v_mov_b64_e32 v[10:11], v[8:9]
	v_mov_b64_e32 v[8:9], v[6:7]
	v_mov_b64_e32 v[6:7], v[4:5]
	v_mov_b64_e32 v[4:5], v[2:3]
	v_mov_b64_e32 v[2:3], v[0:1]
	v_readlane_b32 s14, v253, 4
	v_readlane_b32 s15, v253, 5
	v_readlane_b32 s16, v253, 6
	v_readlane_b32 s17, v253, 7
	v_readlane_b32 s18, v253, 8
	v_readlane_b32 s19, v253, 9
	v_readlane_b32 s20, v253, 10
	v_readlane_b32 s21, v253, 11
	v_readlane_b32 s24, v253, 14
	v_readlane_b32 s25, v253, 15
	v_readlane_b32 s26, v253, 16
	v_readlane_b32 s27, v253, 17
	s_branch .LBB0_764

.LBB0_764:
	v_add_u32_e32 v0, 1, v184
	v_cmp_lt_i32_e32 vcc, v184, v159
	s_nop 1
	v_cndmask_b32_e32 v182, -1, v0, vcc
	v_cmp_gt_i32_e32 vcc, 0, v182
	s_nop 1
	v_cndmask_b32_e32 v50, v182, v184, vcc
	v_lshlrev_b32_e32 v34, 5, v50
	v_ashrrev_i32_e32 v35, 31, v34
	v_lshl_add_u64 v[52:53], v[174:175], 0, v[34:35]
	v_mad_u64_u32 v[54:55], s[40:41], v52, s80, v[178:179]
	v_mov_b32_e32 v0, v55
	v_mad_u64_u32 v[52:53], s[40:41], v53, s80, v[0:1]
	v_ashrrev_i32_e32 v51, 31, v50
	v_mov_b32_e32 v55, v52
	v_lshlrev_b64 v[50:51], 12, v[50:51]
	v_lshl_add_u64 v[50:51], v[176:177], 0, v[50:51]
	s_add_u32 m0, s98, 0x1000
	v_mad_i64_i32 v[232:233], s[100:101], v224, s99, v[54:55]
	v_add_u32_e32 v232, v228, v232
	global_load_lds_dwordx4 v[232:233], off
	s_add_u32 m0, s98, 0x1400
	v_mad_i64_i32 v[232:233], s[100:101], v225, s99, v[54:55]
	v_add_u32_e32 v232, v229, v232
	global_load_lds_dwordx4 v[232:233], off
	s_add_u32 m0, s98, 0x1800
	v_mad_i64_i32 v[232:233], s[100:101], v226, s99, v[54:55]
	v_add_u32_e32 v232, v228, v232
	global_load_lds_dwordx4 v[232:233], off
	s_add_u32 m0, s98, 0x1c00
	v_mad_i64_i32 v[232:233], s[100:101], v227, s99, v[54:55]
	v_add_u32_e32 v232, v229, v232
	global_load_lds_dwordx4 v[232:233], off
	v_and_b32_e32 v230, 63, v199
	v_lshlrev_b32_e32 v230, 4, v230
	v_sub_u32_e32 v230, 0, v230
	v_ashrrev_i32_e32 v231, 31, v230
	v_lshl_add_u64 v[230:231], v[50:51], 0, v[230:231]
	global_load_dwordx4 v[126:129], v[230:231], off
	global_load_dwordx4 v[122:125], v[230:231], off offset:1024
	global_load_dwordx4 v[118:121], v[230:231], off offset:2048
	global_load_dwordx4 v[114:117], v[230:231], off offset:3072
	s_waitcnt vmcnt(12)
	ds_read_b128 v[142:145], v234
	ds_read_b128 v[134:137], v235
	ds_read_b128 v[130:133], v236
	ds_read_b128 v[138:141], v237
	s_waitcnt lgkmcnt(3)
	v_mfma_f32_32x32x16_bf16 v[34:49], v[142:145], v[94:97], 0
	v_cmp_lt_i32_e64 s[40:41], -1, v182
	s_waitcnt lgkmcnt(2)
	v_mfma_f32_32x32x16_bf16 v[34:49], v[134:137], v[86:89], v[34:49]
	s_waitcnt lgkmcnt(1)
	v_mfma_f32_32x32x16_bf16 v[34:49], v[130:133], v[82:85], v[34:49]
	s_waitcnt lgkmcnt(0)
	v_mfma_f32_32x32x16_bf16 v[34:49], v[138:141], v[90:93], v[34:49]
	s_nop 11
	v_max3_f32 v0, v34, v35, v36
	v_max3_f32 v50, v37, v38, v39
	v_max3_f32 v51, v40, v41, v42
	v_max3_f32 v52, v43, v44, v45
	v_max3_f32 v53, v46, v47, v48
	v_max3_f32 v0, v0, v50, v49
	v_max3_f32 v51, v51, v52, v53
	v_max_f32_e32 v0, v0, v51
	v_mov_b32_e32 v50, v0
	s_nop 1
	v_permlane32_swap_b32_e32 v0, v50
	v_max_f32_e32 v0, v0, v50
	v_add_f32_e32 v50, 0x41800000, v183
	v_cmp_gt_f32_e32 vcc, v0, v50
	s_cbranch_vccz .LBB0_766
	s_nop 0
	v_cndmask_b32_e32 v180, v183, v0, vcc
	v_sub_f32_e32 v0, v183, v180
	v_exp_f32_e32 v0, v0
	s_nop 0
	v_mul_f32_e32 v71, v71, v0
	v_pk_mul_f32 v[32:33], v[32:33], v[0:1] op_sel_hi:[1,0]
	v_pk_mul_f32 v[30:31], v[30:31], v[0:1] op_sel_hi:[1,0]
	v_pk_mul_f32 v[28:29], v[28:29], v[0:1] op_sel_hi:[1,0]
	v_pk_mul_f32 v[26:27], v[26:27], v[0:1] op_sel_hi:[1,0]
	v_pk_mul_f32 v[24:25], v[24:25], v[0:1] op_sel_hi:[1,0]
	v_pk_mul_f32 v[22:23], v[22:23], v[0:1] op_sel_hi:[1,0]
	v_pk_mul_f32 v[20:21], v[20:21], v[0:1] op_sel_hi:[1,0]
	v_pk_mul_f32 v[18:19], v[18:19], v[0:1] op_sel_hi:[1,0]
	v_pk_mul_f32 v[16:17], v[16:17], v[0:1] op_sel_hi:[1,0]
	v_pk_mul_f32 v[14:15], v[14:15], v[0:1] op_sel_hi:[1,0]
	v_pk_mul_f32 v[12:13], v[12:13], v[0:1] op_sel_hi:[1,0]
	v_pk_mul_f32 v[10:11], v[10:11], v[0:1] op_sel_hi:[1,0]
	v_pk_mul_f32 v[8:9], v[8:9], v[0:1] op_sel_hi:[1,0]
	v_pk_mul_f32 v[6:7], v[6:7], v[0:1] op_sel_hi:[1,0]
	v_pk_mul_f32 v[4:5], v[4:5], v[0:1] op_sel_hi:[1,0]
	v_pk_mul_f32 v[2:3], v[2:3], v[0:1] op_sel_hi:[1,0]
	s_branch .LBB0_767

.LBB0_767:
	v_pk_add_f32 v[34:35], v[34:35], v[180:181] op_sel_hi:[1,0] neg_lo:[0,1] neg_hi:[0,1]
	v_pk_add_f32 v[36:37], v[36:37], v[180:181] op_sel_hi:[1,0] neg_lo:[0,1] neg_hi:[0,1]
	v_exp_f32_e32 v50, v34
	v_exp_f32_e32 v51, v35
	v_exp_f32_e32 v52, v36
	v_exp_f32_e32 v53, v37
	v_pk_add_f32 v[36:37], v[38:39], v[180:181] op_sel_hi:[1,0] neg_lo:[0,1] neg_hi:[0,1]
	v_pk_add_f32 v[34:35], v[50:51], 0 op_sel_hi:[1,0]
	v_exp_f32_e32 v38, v36
	v_exp_f32_e32 v39, v37
	v_pk_add_f32 v[36:37], v[40:41], v[180:181] op_sel_hi:[1,0] neg_lo:[0,1] neg_hi:[0,1]
	v_pk_add_f32 v[40:41], v[42:43], v[180:181] op_sel_hi:[1,0] neg_lo:[0,1] neg_hi:[0,1]
	v_exp_f32_e32 v36, v36
	v_exp_f32_e32 v37, v37
	v_exp_f32_e32 v40, v40
	v_exp_f32_e32 v41, v41
	v_pk_add_f32 v[42:43], v[44:45], v[180:181] op_sel_hi:[1,0] neg_lo:[0,1] neg_hi:[0,1]
	v_pk_add_f32 v[34:35], v[52:53], v[34:35]
	v_exp_f32_e32 v42, v42
	v_exp_f32_e32 v43, v43
	v_pk_add_f32 v[44:45], v[46:47], v[180:181] op_sel_hi:[1,0] neg_lo:[0,1] neg_hi:[0,1]
	v_pk_add_f32 v[34:35], v[38:39], v[34:35]
	v_exp_f32_e32 v44, v44
	v_exp_f32_e32 v45, v45
	v_pk_add_f32 v[46:47], v[48:49], v[180:181] op_sel_hi:[1,0] neg_lo:[0,1] neg_hi:[0,1]
	v_pk_add_f32 v[34:35], v[36:37], v[34:35]
	v_exp_f32_e32 v46, v46
	v_exp_f32_e32 v47, v47
	v_pk_add_f32 v[34:35], v[40:41], v[34:35]
	v_cvt_pk_bf16_f32 v37, v36, v37
	v_pk_add_f32 v[34:35], v[42:43], v[34:35]
	v_cvt_pk_bf16_f32 v36, v38, v39
	v_pk_add_f32 v[34:35], v[44:45], v[34:35]
	v_cvt_pk_bf16_f32 v73, v46, v47
	v_pk_add_f32 v[34:35], v[46:47], v[34:35]
	v_cvt_pk_bf16_f32 v72, v44, v45
	v_pk_add_f32 v[34:35], v[34:35], v[34:35] op_sel:[0,1] op_sel_hi:[1,0]
	v_cvt_pk_bf16_f32 v70, v40, v41
	v_mov_b32_e32 v0, v34
	s_nop 1
	v_permlane32_swap_b32_e32 v34, v0
	v_add_f32_e32 v0, v34, v0
	v_cvt_pk_bf16_f32 v35, v52, v53
	v_cvt_pk_bf16_f32 v34, v50, v51
	v_add_f32_e32 v169, v71, v0
	v_cvt_pk_bf16_f32 v71, v42, v43
	s_waitcnt vmcnt(11)
	v_mfma_f32_32x32x16_bf16 v[2:17], v[110:113], v[34:37], v[2:17]
	s_mov_b64 s[54:55], -1
	s_or_b64 s[50:51], s[50:51], exec
	s_waitcnt vmcnt(9)
	v_mfma_f32_32x32x16_bf16 v[18:33], v[102:105], v[34:37], v[18:33]
	s_nop 7
	v_mov_b64_e32 v[64:65], v[16:17]
	v_mov_b64_e32 v[62:63], v[14:15]
	v_mov_b64_e32 v[60:61], v[12:13]
	v_mov_b64_e32 v[58:59], v[10:11]
	v_mov_b64_e32 v[56:57], v[8:9]
	v_mov_b64_e32 v[54:55], v[6:7]
	v_mov_b64_e32 v[52:53], v[4:5]
	v_mov_b64_e32 v[48:49], v[32:33]
	v_mov_b64_e32 v[50:51], v[2:3]
	v_mov_b64_e32 v[46:47], v[30:31]
	v_mov_b64_e32 v[44:45], v[28:29]
	v_mov_b64_e32 v[42:43], v[26:27]
	v_mov_b64_e32 v[40:41], v[24:25]
	v_mov_b64_e32 v[38:39], v[22:23]
	v_mov_b64_e32 v[36:37], v[20:21]
	v_mov_b64_e32 v[34:35], v[18:19]
	v_mfma_f32_32x32x16_bf16 v[50:65], v[106:109], v[70:73], v[50:65]
	s_waitcnt vmcnt(8)
	v_mfma_f32_32x32x16_bf16 v[34:49], v[98:101], v[70:73], v[34:49]
	s_and_saveexec_b64 s[52:53], s[40:41]
	s_cbranch_execz .LBB0_763
	v_add_u32_e32 v184, 1, v182
	v_cmp_lt_u32_e32 vcc, v182, v159
	v_mov_b32_e32 v3, v1
	s_waitcnt vmcnt(4)
	ds_read_b128 v[66:69], v234 offset:4096
	ds_read_b128 v[154:157], v235 offset:4096
	ds_read_b128 v[150:153], v236 offset:4096
	ds_read_b128 v[146:149], v237 offset:4096
	s_waitcnt lgkmcnt(3)
	v_mfma_f32_32x32x16_bf16 v[66:81], v[66:69], v[94:97], 0
	v_cndmask_b32_e32 v2, v182, v184, vcc
	v_lshlrev_b32_e32 v0, 5, v2
	v_lshl_add_u64 v[4:5], v[174:175], 0, v[0:1]
	v_mad_u64_u32 v[6:7], s[40:41], v4, s80, v[178:179]
	v_mov_b32_e32 v0, v7
	v_mad_u64_u32 v[4:5], s[40:41], v5, s80, v[0:1]
	v_mov_b32_e32 v7, v4
	v_lshlrev_b64 v[2:3], 12, v[2:3]
	v_lshl_add_u64 v[2:3], v[176:177], 0, v[2:3]
	s_add_u32 m0, s98, 0x0
	v_mad_i64_i32 v[232:233], s[100:101], v224, s99, v[6:7]
	v_add_u32_e32 v232, v228, v232
	global_load_lds_dwordx4 v[232:233], off
	s_add_u32 m0, s98, 0x400
	v_mad_i64_i32 v[232:233], s[100:101], v225, s99, v[6:7]
	v_add_u32_e32 v232, v229, v232
	global_load_lds_dwordx4 v[232:233], off
	s_add_u32 m0, s98, 0x800
	v_mad_i64_i32 v[232:233], s[100:101], v226, s99, v[6:7]
	v_add_u32_e32 v232, v228, v232
	global_load_lds_dwordx4 v[232:233], off
	s_add_u32 m0, s98, 0xc00
	v_mad_i64_i32 v[232:233], s[100:101], v227, s99, v[6:7]
	v_add_u32_e32 v232, v229, v232
	global_load_lds_dwordx4 v[232:233], off
	v_and_b32_e32 v230, 63, v199
	v_lshlrev_b32_e32 v230, 4, v230
	v_sub_u32_e32 v230, 0, v230
	v_ashrrev_i32_e32 v231, 31, v230
	v_lshl_add_u64 v[230:231], v[2:3], 0, v[230:231]
	global_load_dwordx4 v[110:113], v[230:231], off
	global_load_dwordx4 v[106:109], v[230:231], off offset:1024
	global_load_dwordx4 v[102:105], v[230:231], off offset:2048
	global_load_dwordx4 v[98:101], v[230:231], off offset:3072
	s_waitcnt lgkmcnt(2)
	v_mfma_f32_32x32x16_bf16 v[66:81], v[154:157], v[86:89], v[66:81]
	v_cmp_ge_u32_e64 s[40:41], v182, v159
	s_waitcnt lgkmcnt(1)
	v_mfma_f32_32x32x16_bf16 v[66:81], v[150:153], v[82:85], v[66:81]
	s_waitcnt lgkmcnt(0)
	v_mfma_f32_32x32x16_bf16 v[66:81], v[146:149], v[90:93], v[66:81]
	s_nop 11
	v_max3_f32 v0, v66, v67, v68
	v_max3_f32 v2, v69, v70, v71
	v_max3_f32 v3, v72, v73, v74
	v_max3_f32 v4, v75, v76, v77
	v_max3_f32 v5, v78, v79, v80
	v_max3_f32 v0, v0, v2, v81
	v_max3_f32 v3, v3, v4, v5
	v_max_f32_e32 v0, v0, v3
	v_mov_b32_e32 v2, v0
	s_nop 1
	v_permlane32_swap_b32_e32 v0, v2
	v_max_f32_e32 v0, v0, v2
	v_add_f32_e32 v2, 0x41800000, v180
	v_cmp_gt_f32_e32 vcc, v0, v2
	s_cbranch_vccnz .LBB0_761
	v_mov_b64_e32 v[182:183], v[180:181]
	v_mov_b32_e32 v0, v169
	v_mov_b32_e32 v183, v180
	v_mov_b32_e32 v2, v50
	v_mov_b32_e32 v3, v51
	v_mov_b32_e32 v4, v52
	v_mov_b32_e32 v5, v53
	v_mov_b32_e32 v6, v54
	v_mov_b32_e32 v7, v55
	v_mov_b32_e32 v8, v56
	v_mov_b32_e32 v9, v57
	v_mov_b32_e32 v10, v58
	v_mov_b32_e32 v11, v59
	v_mov_b32_e32 v12, v60
	v_mov_b32_e32 v13, v61
	v_mov_b32_e32 v14, v62
	v_mov_b32_e32 v15, v63
	v_mov_b32_e32 v16, v64
	v_mov_b32_e32 v17, v65
	v_mov_b32_e32 v18, v34
	v_mov_b32_e32 v19, v35
	v_mov_b32_e32 v20, v36
	v_mov_b32_e32 v21, v37
	v_mov_b32_e32 v22, v38
	v_mov_b32_e32 v23, v39
	v_mov_b32_e32 v24, v40
	v_mov_b32_e32 v25, v41
	v_mov_b32_e32 v26, v42
	v_mov_b32_e32 v27, v43
	v_mov_b32_e32 v28, v44
	v_mov_b32_e32 v29, v45
	v_mov_b32_e32 v30, v46
	v_mov_b32_e32 v31, v47
	v_mov_b32_e32 v32, v48
	v_mov_b32_e32 v33, v49
	s_branch .LBB0_762

.LBB0_849:
	s_or_b64 exec, exec, s[44:45]
	v_cmp_lt_i32_e32 vcc, -1, v162
	v_lshlrev_b32_e32 v0, 2, v39
	s_and_saveexec_b64 s[38:39], vcc
	s_xor_b64 s[40:41], exec, s[38:39]
	s_cbranch_execz .LBB0_846
	v_readlane_b32 s12, v253, 2
	v_and_b32_e32 v0, 63, v35
	s_lshl_b64 s[38:39], s[42:43], 19
	v_readlane_b32 s22, v253, 12
	v_mov_b32_e32 v35, v1
	v_readlane_b32 s23, v253, 13
	s_add_u32 s38, s22, s38
	v_lshl_add_u64 v[34:35], s[0:1], 0, v[34:35]
	s_addc_u32 s39, s23, s39
	v_lshlrev_b32_e32 v0, 5, v0
	v_readlane_b32 s12, v254, 43
	v_or_b32_e32 v34, v34, v38
	v_mov_b64_e32 v[36:37], s[66:67]
	v_lshl_add_u64 v[166:167], s[38:39], 0, v[0:1]
	v_or_b32_e32 v0, s12, v40
	v_mad_u64_u32 v[36:37], s[38:39], v34, s80, v[36:37]
	v_mad_i32_i24 v37, v35, s80, v37
	v_lshlrev_b32_e32 v34, 1, v0
	v_mov_b32_e32 v35, v1
	v_mov_b32_e32 v163, v1
	v_lshl_add_u64 v[36:37], v[36:37], 0, v[34:35]
	v_lshlrev_b64 v[40:41], 12, v[162:163]
	v_lshl_add_u64 v[40:41], v[166:167], 0, v[40:41]
	v_and_b32_e32 v238, 63, v199
	v_lshrrev_b32_e32 v239, 3, v238
	v_and_b32_e32 v240, 31, v238
	v_sub_u32_e32 v224, v239, v240
	v_add_u32_e32 v225, 8, v224
	v_add_u32_e32 v226, 16, v224
	v_add_u32_e32 v227, 24, v224
	v_lshrrev_b32_e32 v241, 5, v238
	v_and_b32_e32 v242, 7, v238
	v_lshrrev_b32_e32 v243, 4, v238
	v_xor_b32_e32 v228, v242, v243
	v_xor_b32_e32 v229, 4, v228
	v_sub_u32_e32 v228, v228, v241
	v_sub_u32_e32 v229, v229, v241
	v_lshlrev_b32_e32 v228, 4, v228
	v_lshlrev_b32_e32 v229, 4, v229
	v_lshrrev_b32_e32 v250, 6, v199
	v_lshlrev_b32_e32 v250, 13, v250
	v_bfe_u32 v251, v238, 1, 3
	v_xor_b32_e32 v251, v251, v241
	v_lshlrev_b32_e32 v251, 4, v251
	v_lshl_add_u32 v251, v240, 7, v251
	v_add_u32_e32 v234, v250, v251
	v_xor_b32_e32 v235, 0x20, v234
	v_xor_b32_e32 v236, 0x40, v234
	v_xor_b32_e32 v237, 0x60, v234
	v_readfirstlane_b32 s98, v250
	s_mov_b32 s99, 0x1c00
	s_add_u32 m0, s98, 0x0
	v_mad_i64_i32 v[232:233], s[100:101], v224, s99, v[36:37]
	v_add_u32_e32 v232, v228, v232
	global_load_lds_dwordx4 v[232:233], off
	s_add_u32 m0, s98, 0x400
	v_mad_i64_i32 v[232:233], s[100:101], v225, s99, v[36:37]
	v_add_u32_e32 v232, v229, v232
	global_load_lds_dwordx4 v[232:233], off
	s_add_u32 m0, s98, 0x800
	v_mad_i64_i32 v[232:233], s[100:101], v226, s99, v[36:37]
	v_add_u32_e32 v232, v228, v232
	global_load_lds_dwordx4 v[232:233], off
	s_add_u32 m0, s98, 0xc00
	v_mad_i64_i32 v[232:233], s[100:101], v227, s99, v[36:37]
	v_add_u32_e32 v232, v229, v232
	global_load_lds_dwordx4 v[232:233], off
	v_and_b32_e32 v230, 63, v199
	v_lshlrev_b32_e32 v230, 4, v230
	v_sub_u32_e32 v230, 0, v230
	v_ashrrev_i32_e32 v231, 31, v230
	v_lshl_add_u64 v[230:231], v[40:41], 0, v[230:231]
	global_load_dwordx4 v[110:113], v[230:231], off
	global_load_dwordx4 v[106:109], v[230:231], off offset:1024
	global_load_dwordx4 v[102:105], v[230:231], off offset:2048
	global_load_dwordx4 v[98:101], v[230:231], off offset:3072
	v_lshl_add_u64 v[170:171], s[66:67], 0, v[34:35]
	v_and_b32_e32 v34, 0x7ffffff8, v162
	v_lshlrev_b32_e32 v0, 2, v39
	v_cmp_ne_u32_e32 vcc, v34, v162
	v_or_b32_e32 v163, 0x186a0, v0
	v_or_b32_e32 v172, 0x186a1, v0
	v_or_b32_e32 v173, 0x186a2, v0
	v_or_b32_e32 v174, 0x186a3, v0
	v_or_b32_e32 v175, 0x186a8, v0
	v_or_b32_e32 v176, 0x186a9, v0
	v_or_b32_e32 v177, 0x186aa, v0
	v_or_b32_e32 v178, 0x186ab, v0
	v_or_b32_e32 v179, 0x186b0, v0
	v_or_b32_e32 v180, 0x186b1, v0
	v_or_b32_e32 v181, 0x186b2, v0
	v_or_b32_e32 v182, 0x186b3, v0
	v_or_b32_e32 v183, 0x186b8, v0
	v_or_b32_e32 v184, 0x186b9, v0
	v_or_b32_e32 v185, 0x186ba, v0
	v_or_b32_e32 v186, 0x186bb, v0
	v_or_b32_e32 v168, s0, v38
	v_mov_b32_e32 v169, s1
	v_or_b32_e32 v187, 0x186a0, v38
	v_cndmask_b32_e32 v188, -1, v34, vcc
	s_mov_b64 s[44:45], 0
	v_mov_b32_e32 v190, v162
	v_readlane_b32 s13, v253, 3
	v_readlane_b32 s14, v253, 4
	v_readlane_b32 s15, v253, 5
	v_readlane_b32 s16, v253, 6
	v_readlane_b32 s17, v253, 7
	v_readlane_b32 s18, v253, 8
	v_readlane_b32 s19, v253, 9
	v_readlane_b32 s20, v253, 10
	v_readlane_b32 s21, v253, 11
	v_readlane_b32 s24, v253, 14
	v_readlane_b32 s25, v253, 15
	v_readlane_b32 s26, v253, 16
	v_readlane_b32 s27, v253, 17
	s_branch .LBB0_854

.LBB0_854:
	v_add_u32_e32 v34, 1, v190
	v_cmp_lt_i32_e32 vcc, v34, v162
	s_nop 1
	v_cndmask_b32_e32 v34, -1, v34, vcc
	v_cmp_eq_u32_e32 vcc, v190, v162
	s_nop 1
	v_cndmask_b32_e32 v71, v34, v188, vcc
	v_cmp_gt_i32_e64 s[0:1], 0, v71
	v_cmp_lt_i32_e64 s[38:39], -1, v71
	s_nop 0
	v_cndmask_b32_e64 v50, v71, v190, s[0:1]
	v_lshlrev_b32_e32 v34, 5, v50
	v_ashrrev_i32_e32 v35, 31, v34
	v_lshl_add_u64 v[52:53], v[168:169], 0, v[34:35]
	v_mad_u64_u32 v[54:55], s[0:1], v52, s80, v[170:171]
	v_mov_b32_e32 v52, v55
	v_mad_u64_u32 v[52:53], s[0:1], v53, s80, v[52:53]
	v_ashrrev_i32_e32 v51, 31, v50
	v_mov_b32_e32 v55, v52
	v_lshlrev_b64 v[50:51], 12, v[50:51]
	v_lshl_add_u64 v[50:51], v[166:167], 0, v[50:51]
	s_add_u32 m0, s98, 0x1000
	v_mad_i64_i32 v[232:233], s[100:101], v224, s99, v[54:55]
	v_add_u32_e32 v232, v228, v232
	global_load_lds_dwordx4 v[232:233], off
	s_add_u32 m0, s98, 0x1400
	v_mad_i64_i32 v[232:233], s[100:101], v225, s99, v[54:55]
	v_add_u32_e32 v232, v229, v232
	global_load_lds_dwordx4 v[232:233], off
	s_add_u32 m0, s98, 0x1800
	v_mad_i64_i32 v[232:233], s[100:101], v226, s99, v[54:55]
	v_add_u32_e32 v232, v228, v232
	global_load_lds_dwordx4 v[232:233], off
	s_add_u32 m0, s98, 0x1c00
	v_mad_i64_i32 v[232:233], s[100:101], v227, s99, v[54:55]
	v_add_u32_e32 v232, v229, v232
	global_load_lds_dwordx4 v[232:233], off
	v_and_b32_e32 v230, 63, v199
	v_lshlrev_b32_e32 v230, 4, v230
	v_sub_u32_e32 v230, 0, v230
	v_ashrrev_i32_e32 v231, 31, v230
	v_lshl_add_u64 v[230:231], v[50:51], 0, v[230:231]
	global_load_dwordx4 v[142:145], v[230:231], off
	global_load_dwordx4 v[126:129], v[230:231], off offset:1024
	global_load_dwordx4 v[118:121], v[230:231], off offset:2048
	global_load_dwordx4 v[114:117], v[230:231], off offset:3072
	s_waitcnt vmcnt(12)
	ds_read_b128 v[138:141], v234
	ds_read_b128 v[130:133], v235
	ds_read_b128 v[122:125], v236
	ds_read_b128 v[134:137], v237
	s_waitcnt lgkmcnt(3)
	v_mfma_f32_32x32x16_bf16 v[34:49], v[138:141], v[90:93], 0
	v_cndmask_b32_e32 v50, v219, v187, vcc
	v_cmp_gt_u32_e32 vcc, s9, v50
	s_waitcnt lgkmcnt(2)
	v_mfma_f32_32x32x16_bf16 v[34:49], v[130:133], v[82:85], v[34:49]
	s_waitcnt lgkmcnt(1)
	v_mfma_f32_32x32x16_bf16 v[34:49], v[122:125], v[86:89], v[34:49]
	s_waitcnt lgkmcnt(0)
	v_mfma_f32_32x32x16_bf16 v[34:49], v[134:137], v[94:97], v[34:49]
	s_cbranch_vccz .LBB0_856
	v_cmp_le_u32_e32 vcc, v163, v50
	s_nop 9
	v_cndmask_b32_e32 v34, v212, v34, vcc
	v_cmp_le_u32_e32 vcc, v172, v50
	s_nop 1
	v_cndmask_b32_e32 v35, v212, v35, vcc
	v_cmp_le_u32_e32 vcc, v173, v50
	s_nop 1
	v_cndmask_b32_e32 v36, v212, v36, vcc
	v_cmp_le_u32_e32 vcc, v174, v50
	s_nop 1
	v_cndmask_b32_e32 v37, v212, v37, vcc
	v_cmp_le_u32_e32 vcc, v175, v50
	s_nop 1
	v_cndmask_b32_e32 v38, v212, v38, vcc
	v_cmp_le_u32_e32 vcc, v176, v50
	s_nop 1
	v_cndmask_b32_e32 v39, v212, v39, vcc
	v_cmp_le_u32_e32 vcc, v177, v50
	s_nop 1
	v_cndmask_b32_e32 v40, v212, v40, vcc
	v_cmp_le_u32_e32 vcc, v178, v50
	s_nop 1
	v_cndmask_b32_e32 v41, v212, v41, vcc
	v_cmp_le_u32_e32 vcc, v179, v50
	s_nop 1
	v_cndmask_b32_e32 v42, v212, v42, vcc
	v_cmp_le_u32_e32 vcc, v180, v50
	s_nop 1
	v_cndmask_b32_e32 v43, v212, v43, vcc
	v_cmp_le_u32_e32 vcc, v181, v50
	s_nop 1
	v_cndmask_b32_e32 v44, v212, v44, vcc
	v_cmp_le_u32_e32 vcc, v182, v50
	s_nop 1
	v_cndmask_b32_e32 v45, v212, v45, vcc
	v_cmp_le_u32_e32 vcc, v183, v50
	s_nop 1
	v_cndmask_b32_e32 v46, v212, v46, vcc
	v_cmp_le_u32_e32 vcc, v184, v50
	s_nop 1
	v_cndmask_b32_e32 v47, v212, v47, vcc
	v_cmp_le_u32_e32 vcc, v185, v50
	s_nop 1
	v_cndmask_b32_e32 v48, v212, v48, vcc
	v_cmp_le_u32_e32 vcc, v186, v50
	s_nop 1
	v_cndmask_b32_e32 v49, v212, v49, vcc

.LBB0_858:
	v_pk_add_f32 v[34:35], v[34:35], v[164:165] op_sel_hi:[1,0] neg_lo:[0,1] neg_hi:[0,1]
	v_pk_add_f32 v[36:37], v[36:37], v[164:165] op_sel_hi:[1,0] neg_lo:[0,1] neg_hi:[0,1]
	v_exp_f32_e32 v34, v34
	v_exp_f32_e32 v35, v35
	v_exp_f32_e32 v36, v36
	v_exp_f32_e32 v37, v37
	v_pk_add_f32 v[38:39], v[38:39], v[164:165] op_sel_hi:[1,0] neg_lo:[0,1] neg_hi:[0,1]
	v_pk_add_f32 v[40:41], v[40:41], v[164:165] op_sel_hi:[1,0] neg_lo:[0,1] neg_hi:[0,1]
	v_exp_f32_e32 v38, v38
	v_exp_f32_e32 v39, v39
	v_exp_f32_e32 v40, v40
	v_exp_f32_e32 v41, v41
	v_pk_add_f32 v[42:43], v[42:43], v[164:165] op_sel_hi:[1,0] neg_lo:[0,1] neg_hi:[0,1]
	v_pk_add_f32 v[50:51], v[34:35], 0 op_sel_hi:[1,0]
	v_exp_f32_e32 v42, v42
	v_exp_f32_e32 v43, v43
	v_pk_add_f32 v[44:45], v[44:45], v[164:165] op_sel_hi:[1,0] neg_lo:[0,1] neg_hi:[0,1]
	v_pk_add_f32 v[50:51], v[36:37], v[50:51]
	v_exp_f32_e32 v44, v44
	v_exp_f32_e32 v45, v45
	v_pk_add_f32 v[46:47], v[46:47], v[164:165] op_sel_hi:[1,0] neg_lo:[0,1] neg_hi:[0,1]
	v_pk_add_f32 v[50:51], v[38:39], v[50:51]
	v_exp_f32_e32 v46, v46
	v_exp_f32_e32 v47, v47
	v_pk_add_f32 v[48:49], v[48:49], v[164:165] op_sel_hi:[1,0] neg_lo:[0,1] neg_hi:[0,1]
	v_pk_add_f32 v[50:51], v[40:41], v[50:51]
	v_exp_f32_e32 v48, v48
	v_exp_f32_e32 v49, v49
	v_pk_add_f32 v[50:51], v[42:43], v[50:51]
	v_cvt_pk_bf16_f32 v53, v40, v41
	v_pk_add_f32 v[50:51], v[44:45], v[50:51]
	v_cvt_pk_bf16_f32 v52, v38, v39
	v_pk_add_f32 v[50:51], v[46:47], v[50:51]
	v_cvt_pk_bf16_f32 v75, v48, v49
	v_pk_add_f32 v[50:51], v[48:49], v[50:51]
	v_cvt_pk_bf16_f32 v74, v46, v47
	v_pk_add_f32 v[50:51], v[50:51], v[50:51] op_sel:[0,1] op_sel_hi:[1,0]
	v_cvt_pk_bf16_f32 v73, v44, v45
	v_mov_b32_e32 v51, v50
	s_nop 1
	v_permlane32_swap_b32_e32 v50, v51
	v_add_f32_e32 v50, v50, v51
	v_add_f32_e32 v189, v70, v50
	v_cvt_pk_bf16_f32 v51, v36, v37
	v_cvt_pk_bf16_f32 v50, v34, v35
	v_cvt_pk_bf16_f32 v72, v42, v43
	s_mov_b64 s[0:1], -1
	s_waitcnt vmcnt(11)
	v_mfma_f32_32x32x16_bf16 v[18:33], v[110:113], v[50:53], v[18:33]
	s_or_b64 s[46:47], s[46:47], exec
	s_waitcnt vmcnt(9)
	v_mfma_f32_32x32x16_bf16 v[2:17], v[102:105], v[50:53], v[2:17]
	s_nop 8
	v_mov_b64_e32 v[48:49], v[32:33]
	v_mov_b64_e32 v[46:47], v[30:31]
	v_mov_b64_e32 v[44:45], v[28:29]
	v_mov_b64_e32 v[42:43], v[26:27]
	v_mov_b64_e32 v[40:41], v[24:25]
	v_mov_b64_e32 v[38:39], v[22:23]
	v_mov_b64_e32 v[36:37], v[20:21]
	v_mov_b64_e32 v[64:65], v[16:17]
	v_mov_b64_e32 v[34:35], v[18:19]
	v_mov_b64_e32 v[62:63], v[14:15]
	v_mov_b64_e32 v[60:61], v[12:13]
	v_mov_b64_e32 v[58:59], v[10:11]
	v_mov_b64_e32 v[56:57], v[8:9]
	v_mov_b64_e32 v[54:55], v[6:7]
	v_mov_b64_e32 v[52:53], v[4:5]
	v_mov_b64_e32 v[50:51], v[2:3]
	v_mfma_f32_32x32x16_bf16 v[34:49], v[106:109], v[72:75], v[34:49]
	s_waitcnt vmcnt(8)
	v_mfma_f32_32x32x16_bf16 v[50:65], v[98:101], v[72:75], v[50:65]
	s_and_saveexec_b64 s[48:49], s[38:39]
	s_cbranch_execz .LBB0_853
	v_add_u32_e32 v2, 1, v71
	v_cmp_lt_i32_e32 vcc, v2, v162
	s_nop 1
	v_cndmask_b32_e32 v2, -1, v2, vcc
	v_cmp_eq_u32_e32 vcc, v71, v162
	s_nop 1
	v_cndmask_b32_e32 v190, v2, v188, vcc
	v_cmp_lt_i32_e64 s[0:1], -1, v190
	v_cmp_gt_i32_e64 s[38:39], 0, v190
	s_nop 0
	v_cndmask_b32_e64 v2, v71, v190, s[0:1]
	v_lshlrev_b32_e32 v4, 5, v2
	v_ashrrev_i32_e32 v5, 31, v4
	v_lshl_add_u64 v[4:5], v[168:169], 0, v[4:5]
	v_mad_u64_u32 v[6:7], s[0:1], v4, s80, v[170:171]
	v_mov_b32_e32 v4, v7
	v_mad_u64_u32 v[4:5], s[0:1], v5, s80, v[4:5]
	v_ashrrev_i32_e32 v3, 31, v2
	v_mov_b32_e32 v7, v4
	v_lshlrev_b64 v[2:3], 12, v[2:3]
	v_lshl_add_u64 v[2:3], v[166:167], 0, v[2:3]
	s_add_u32 m0, s98, 0x0
	v_mad_i64_i32 v[232:233], s[100:101], v224, s99, v[6:7]
	v_add_u32_e32 v232, v228, v232
	global_load_lds_dwordx4 v[232:233], off
	s_add_u32 m0, s98, 0x400
	v_mad_i64_i32 v[232:233], s[100:101], v225, s99, v[6:7]
	v_add_u32_e32 v232, v229, v232
	global_load_lds_dwordx4 v[232:233], off
	s_add_u32 m0, s98, 0x800
	v_mad_i64_i32 v[232:233], s[100:101], v226, s99, v[6:7]
	v_add_u32_e32 v232, v228, v232
	global_load_lds_dwordx4 v[232:233], off
	s_add_u32 m0, s98, 0xc00
	v_mad_i64_i32 v[232:233], s[100:101], v227, s99, v[6:7]
	v_add_u32_e32 v232, v229, v232
	global_load_lds_dwordx4 v[232:233], off
	v_and_b32_e32 v230, 63, v199
	v_lshlrev_b32_e32 v230, 4, v230
	v_sub_u32_e32 v230, 0, v230
	v_ashrrev_i32_e32 v231, 31, v230
	v_lshl_add_u64 v[230:231], v[2:3], 0, v[230:231]
	global_load_dwordx4 v[110:113], v[230:231], off
	global_load_dwordx4 v[106:109], v[230:231], off offset:1024
	global_load_dwordx4 v[102:105], v[230:231], off offset:2048
	global_load_dwordx4 v[98:101], v[230:231], off offset:3072
	s_waitcnt vmcnt(12)
	ds_read_b128 v[66:69], v234 offset:4096
	ds_read_b128 v[154:157], v235 offset:4096
	ds_read_b128 v[150:153], v236 offset:4096
	ds_read_b128 v[146:149], v237 offset:4096
	s_waitcnt lgkmcnt(3)
	v_mfma_f32_32x32x16_bf16 v[66:81], v[66:69], v[90:93], 0
	v_cndmask_b32_e32 v2, v219, v187, vcc
	v_cmp_gt_u32_e32 vcc, s9, v2
	s_waitcnt lgkmcnt(2)
	v_mfma_f32_32x32x16_bf16 v[66:81], v[154:157], v[82:85], v[66:81]
	s_waitcnt lgkmcnt(1)
	v_mfma_f32_32x32x16_bf16 v[66:81], v[150:153], v[86:89], v[66:81]
	s_waitcnt lgkmcnt(0)
	v_mfma_f32_32x32x16_bf16 v[66:81], v[146:149], v[94:97], v[66:81]
	s_cbranch_vccz .LBB0_861
	v_cmp_le_u32_e32 vcc, v163, v2
	s_nop 9
	v_cndmask_b32_e32 v66, v212, v66, vcc
	v_cmp_le_u32_e32 vcc, v172, v2
	s_nop 1
	v_cndmask_b32_e32 v67, v212, v67, vcc
	v_cmp_le_u32_e32 vcc, v173, v2
	s_nop 1
	v_cndmask_b32_e32 v68, v212, v68, vcc
	v_cmp_le_u32_e32 vcc, v174, v2
	s_nop 1
	v_cndmask_b32_e32 v69, v212, v69, vcc
	v_cmp_le_u32_e32 vcc, v175, v2
	s_nop 1
	v_cndmask_b32_e32 v70, v212, v70, vcc
	v_cmp_le_u32_e32 vcc, v176, v2
	s_nop 1
	v_cndmask_b32_e32 v71, v212, v71, vcc
	v_cmp_le_u32_e32 vcc, v177, v2
	s_nop 1
	v_cndmask_b32_e32 v72, v212, v72, vcc
	v_cmp_le_u32_e32 vcc, v178, v2
	s_nop 1
	v_cndmask_b32_e32 v73, v212, v73, vcc
	v_cmp_le_u32_e32 vcc, v179, v2
	s_nop 1
	v_cndmask_b32_e32 v74, v212, v74, vcc
	v_cmp_le_u32_e32 vcc, v180, v2
	s_nop 1
	v_cndmask_b32_e32 v75, v212, v75, vcc
	v_cmp_le_u32_e32 vcc, v181, v2
	s_nop 1
	v_cndmask_b32_e32 v76, v212, v76, vcc
	v_cmp_le_u32_e32 vcc, v182, v2
	s_nop 1
	v_cndmask_b32_e32 v77, v212, v77, vcc
	v_cmp_le_u32_e32 vcc, v183, v2
	s_nop 1
	v_cndmask_b32_e32 v78, v212, v78, vcc
	v_cmp_le_u32_e32 vcc, v184, v2
	s_nop 1
	v_cndmask_b32_e32 v79, v212, v79, vcc
	v_cmp_le_u32_e32 vcc, v185, v2
	s_nop 1
	v_cndmask_b32_e32 v80, v212, v80, vcc
	v_cmp_le_u32_e32 vcc, v186, v2
	s_nop 1
	v_cndmask_b32_e32 v81, v212, v81, vcc
